# attention loops: DMA issue moved into MFMA body, slimmed DMA slots, hazard nops trimmed, l-sum chains hoisted from latch into MFMA gaps; plus pipelined GEMM k-loop
# speedup vs baseline: 1.0238x; 1.0238x over previous
; template <int DQK, int DV, int NMAPS>
; __device__ __forceinline__ void attn_phase(const AttnArgs& a, unsigned char* smem) {
;     ...
;     auto dma = [&](bool wantk, int kt, int kb, bool wantv, int vt, int vb) {
; #pragma unroll
;       for (int i = 0; i < NDI; ++i) {
;         const int idx = wave + 8 * i;
;         if (idx < NKI) {
;           if (wantk) glds16s(Kg + (size_t)kt * 64 * a.ldk, (unsigned)doff[i], (unsigned)__builtin_amdgcn_readfirstlane(lds0 + kb * KBYTES + idx * 1024));
;         } else if (idx < NKI + NVI) {
;     ...
; #pragma unroll
;       for (int i = 0; i < PD; ++i) issue(i);
; #pragma unroll
;       for (int i = 0; i < NMF; ++i) {
;         issue(i + PD);
;         if (i < NPV) {
;           if (do_pv) {
;             const int js = i / NDT, d = i % NDT;
;             union { unsigned u[4]; bf16x8 v; } cv;
; #pragma unroll
;             for (int k = 0; k < 4; ++k) cv.u[k] = ppu[4 * js + k];
;             int nafter = 0;
; #pragma unroll
;             for (int cc = i + 1; cc <= i + PD; ++cc) {
;               if (cc < NPV) nafter += 2;
;               else if (cc < NMF && do_qk) nafter += ((cc - NPV) & 1) ? 1 : 2;
;             }
;             bf16x8 vfr = fr[i % (PD + 1)];
;             asm volatile("s_waitcnt lgkmcnt(%1)" : "+v"(vfr) : "i"(nafter));
;             o[d] = MFMA32(vfr, cv.v, o[d]);
;           }
;         } else {
;           if (do_qk) {
;             const int qi = i - NPV, ks = qi >> 1, j = qi & 1;
;             if (ks == 0) {
;               f32x16 z;
; #pragma unroll
;               for (int q = 0; q < 16; ++q) z[q] = 0.f;
;               sn[j] = MFMA32(fr[i % (PD + 1)], qv[ks % 3], z);
;             } else sn[j] = MFMA32(fr[i % (PD + 1)], qv[ks % 3], sn[j]);
;           }
;         }
;         const int lo_v = i * 32 / NMF, hi_v = (i + 1) * 32 / NMF;
; #pragma unroll
;         for (int v = lo_v; v < hi_v; ++v) {
;           const float pvv = __builtin_amdgcn_exp2f(sc[v >> 4][v & 15] * c - mc);
;           sc[v >> 4][v & 15] = pvv;
;           ps0 += pvv;
;         }
;         if (i >= NPV) {
;           const int plo = (i == NPV) ? 0 : (lo_v >> 1), phi = hi_v >> 1;
; #pragma unroll
;           for (int pi = plo; pi < phi; ++pi) ppu[pi] = pack2(sc[(2 * pi) >> 4][(2 * pi) & 15], sc[(2 * pi + 1) >> 4][(2 * pi + 1) & 15]);
;         }
;         __builtin_amdgcn_sched_barrier(0);
;       }
;       l = l * alpha + ps0;
.LBB0_157:
	v_add_f32_e32 v73, v73, v88
	v_add_f32_e32 v73, v74, v73
	v_add_f32_e32 v73, v75, v73
	v_add_f32_e32 v73, v76, v73
	v_add_f32_e32 v73, v77, v73
	s_add_u32 s0, s0, 0x60000
	v_add_f32_e32 v73, v78, v73
	s_addc_u32 s1, s1, 0
	s_add_i32 s82, s82, 2
	v_add_f32_e32 v109, v79, v73
	s_waitcnt vmcnt(0)
	s_add_u32 s72, s72, 0x40000
	v_fmac_f32_e32 v109, v110, v72
	s_waitcnt lgkmcnt(0)
	v_max_f32_e32 v72, v165, v165
	v_max_f32_e32 v73, v159, v159
	s_addc_u32 s73, s73, 0
	v_max_f32_e32 v72, v73, v72
	s_cmp_ge_u32 s87, s86
	s_barrier
	s_cbranch_scc1 .LBB0_218
.LBB0_158:
	s_add_i32 s87, s82, -1
	s_cmp_lt_u32 s87, s84
	s_cselect_b64 s[50:51], -1, 0
	v_cndmask_b32_e64 v73, 0, 1, s[50:51]
	v_cmp_ne_u32_e64 s[50:51], 1, v73
.LBB0_186:
	v_max_f32_e32 v72, v72, v72
	v_max_f32_e32 v73, v97, v97
	v_max_f32_e32 v142, v73, v72
	v_sub_f32_e32 v72, v97, v142
	v_mul_f32_e32 v96, 0x3e16c740, v72
	ds_read_b64_tr_b16 v[72:73], v106 offset:0
	ds_read_b64_tr_b16 v[74:75], v106 offset:0x600
	ds_read_b64_tr_b16 v[76:77], v106 offset:64
	ds_read_b64_tr_b16 v[78:79], v106 offset:0x640
	ds_read_b64_tr_b16 v[88:89], v106 offset:0xc00
	ds_read_b64_tr_b16 v[90:91], v106 offset:0x1200
	ds_read_b64_tr_b16 v[92:93], v106 offset:0xc40
	ds_read_b64_tr_b16 v[94:95], v106 offset:0x1240
	s_nop 0
	s_waitcnt lgkmcnt(6)
	v_mul_f32_e32 v97, 0x3e16c740, v142
	v_mfma_f32_32x32x16_bf16 v[16:31], v[72:75], v[84:87], v[16:31]
	v_fma_f32 v48, v48, s80, -v97
	v_exp_f32_e32 v110, v48
	ds_read_b64_tr_b16 v[72:73], v106 offset:0x1800
	ds_read_b64_tr_b16 v[74:75], v106 offset:0x1e00
	s_waitcnt lgkmcnt(6)
	v_fma_f32 v48, v49, s80, -v97
	v_mfma_f32_32x32x16_bf16 v[0:15], v[76:79], v[84:87], v[0:15]
	v_exp_f32_e32 v111, v48
	v_fma_f32 v48, v50, s80, -v97
	v_exp_f32_e32 v112, v48
	ds_read_b64_tr_b16 v[76:77], v106 offset:0x1840
	ds_read_b64_tr_b16 v[78:79], v106 offset:0x1e40
	s_waitcnt lgkmcnt(6)
	v_fma_f32 v48, v51, s80, -v97
	v_mfma_f32_32x32x16_bf16 v[16:31], v[88:91], v[80:83], v[16:31]
	v_exp_f32_e32 v113, v48
	s_and_b64 vcc, exec, s[40:41]
	s_cbranch_vccnz .LBB0_162
	s_and_b64 vcc, exec, s[50:51]
	s_cbranch_vccnz .LBB0_165
	s_add_i32 m0, s25, 0x3400
	s_add_u32 s74, s0, 0xfffd0000
	s_addc_u32 s75, s1, -1
	global_load_lds_dwordx4 v98, s[74:75]
	s_branch .LBB0_165
.LBB0_162:
	s_and_b64 vcc, exec, s[42:43]
	s_cbranch_vccnz .LBB0_165
	s_add_i32 m0, s25, 0x6400
	s_add_u32 s74, s72, 0xfffe0000
	s_addc_u32 s75, s73, -1
	global_load_lds_dwordx4 v98, s[74:75]
.LBB0_165:
	ds_read_b64_tr_b16 v[48:49], v106 offset:0x2400
	ds_read_b64_tr_b16 v[50:51], v106 offset:0x2a00
	s_waitcnt lgkmcnt(6)
	v_fma_f32 v52, v52, s80, -v97
	v_mfma_f32_32x32x16_bf16 v[0:15], v[92:95], v[80:83], v[0:15]
	v_exp_f32_e32 v114, v52
	v_fma_f32 v52, v53, s80, -v97
	v_exp_f32_e32 v115, v52
	ds_read_b64_tr_b16 v[80:81], v106 offset:0x2440
	ds_read_b64_tr_b16 v[82:83], v106 offset:0x2a40
	s_waitcnt lgkmcnt(6)
	v_fma_f32 v52, v54, s80, -v97
	v_mfma_f32_32x32x16_bf16 v[16:31], v[72:75], v[64:67], v[16:31]
	v_exp_f32_e32 v116, v52
	v_fma_f32 v52, v55, s80, -v97
	v_exp_f32_e32 v117, v52
	ds_read_b128 v[72:75], v102
	ds_read_b128 v[126:129], v105 offset:51200
	s_waitcnt lgkmcnt(6)
	v_fma_f32 v52, v56, s80, -v97
	v_mfma_f32_32x32x16_bf16 v[0:15], v[76:79], v[64:67], v[0:15]
	v_exp_f32_e32 v118, v52
	ds_read_b128 v[64:67], v102 offset:6656
	s_waitcnt lgkmcnt(5)
	v_mfma_f32_32x32x16_bf16 v[16:31], v[48:51], v[68:71], v[16:31]
	v_fma_f32 v48, v57, s80, -v97
	v_exp_f32_e32 v119, v48
	v_fma_f32 v48, v58, s80, -v97
	v_exp_f32_e32 v120, v48
	s_and_b64 vcc, exec, s[26:27]
	s_cbranch_vccz .LBB0_169
	s_and_b64 vcc, exec, s[50:51]
	s_cbranch_vccnz .LBB0_172
	s_add_i32 m0, s29, 0x3400
	s_add_u32 s74, s0, 0xfffd0000
	s_addc_u32 s75, s1, -1
	global_load_lds_dwordx4 v99, s[74:75]
	s_branch .LBB0_172
.LBB0_169:
	s_and_b64 vcc, exec, s[44:45]
	s_cbranch_vccnz .LBB0_172
	s_add_i32 m0, s29, 0x6400
	s_add_u32 s74, s72, 0xfffe0000
	s_addc_u32 s75, s73, -1
	global_load_lds_dwordx4 v99, s[74:75]
.LBB0_172:
	ds_read_b128 v[130:133], v102 offset:32
	ds_read_b128 v[134:137], v105 offset:52224
	s_waitcnt lgkmcnt(5)
	v_fma_f32 v48, v59, s80, -v97
	v_mfma_f32_32x32x16_bf16 v[0:15], v[80:83], v[68:71], v[0:15]
	v_exp_f32_e32 v121, v48
	s_waitcnt lgkmcnt(3)
	v_mfma_f32_32x32x16_bf16 v[80:95], v[72:75], v[126:129], 0
	v_fma_f32 v48, v60, s80, -v97
	v_exp_f32_e32 v122, v48
	v_fma_f32 v48, v61, s80, -v97
	ds_read_b128 v[56:59], v102 offset:6688
	v_exp_f32_e32 v123, v48
	v_cvt_pk_bf16_f32 v52, v110, v111
	v_cvt_pk_bf16_f32 v53, v112, v113
	v_cvt_pk_bf16_f32 v54, v114, v115
	v_cvt_pk_bf16_f32 v55, v116, v117
	v_cvt_pk_bf16_f32 v48, v118, v119
	v_cvt_pk_bf16_f32 v49, v120, v121
	v_cvt_pk_bf16_f32 v50, v122, v123
	s_waitcnt lgkmcnt(3)
	v_mfma_f32_32x32x16_bf16 v[64:79], v[64:67], v[126:129], 0
	v_fma_f32 v51, v62, s80, -v97
	ds_read_b128 v[138:141], v102 offset:64
	ds_read_b128 v[144:147], v105 offset:53248
	v_exp_f32_e32 v124, v51
	v_fma_f32 v51, v63, s80, -v97
	v_exp_f32_e32 v125, v51
	s_nop 0
	v_cvt_pk_bf16_f32 v51, v124, v125
	s_waitcnt lgkmcnt(3)
	v_mfma_f32_32x32x16_bf16 v[80:95], v[130:133], v[134:137], v[80:95]
	v_fma_f32 v32, v32, s80, -v97
	ds_read_b128 v[60:63], v102 offset:6720
	v_exp_f32_e32 v126, v32
	s_and_b64 vcc, exec, s[30:31]
	s_cbranch_vccz .LBB0_176
	s_and_b64 vcc, exec, s[50:51]
	s_cbranch_vccnz .LBB0_179
	s_add_i32 m0, s33, 0x3400
	s_add_u32 s74, s0, 0xfffd0000
	s_addc_u32 s75, s1, -1
	global_load_lds_dwordx4 v100, s[74:75]
	s_branch .LBB0_179
.LBB0_176:
	s_and_b64 vcc, exec, s[46:47]
	s_cbranch_vccnz .LBB0_179
	s_add_i32 m0, s33, 0x6400
	s_add_u32 s74, s72, 0xfffe0000
	s_addc_u32 s75, s73, -1
	global_load_lds_dwordx4 v100, s[74:75]
; __device__ __forceinline__ unsigned pack2(float a, float b) { unsigned r; asm("s_nop 1\n\tv_cvt_pk_bf16_f32 %0, %1, %2" : "=v"(r) : "v"(a), "v"(b)); return r; }
; #define MX3(a_, b_, c_) __builtin_fmaxf(__builtin_fmaxf((a_), (b_)), (c_))
; template <int DQK, int DV, int NMAPS>
; __device__ __forceinline__ void attn_phase(const AttnArgs& a, unsigned char* smem) {
;     ...
;     auto rowmax = [&](const f32x16 (&sx)[2]) -> float {
;     ...
;       float mx = MX3(sx[0][0], sx[1][0], sx[0][1]);
;       mx = MX3(mx, sx[1][1], sx[0][2]);
; #pragma unroll
;       for (int q = 2; q < 15; ++q) mx = MX3(mx, sx[1][q], sx[0][q + 1]);
;       mx = __builtin_fmaxf(mx, sx[1][15]);
;     ...
;       return __builtin_fmaxf(mx, __shfl_xor(mx, 32));
;     };
;     ...
;         const int lo_v = i * 32 / NMF, hi_v = (i + 1) * 32 / NMF;
; #pragma unroll
;         for (int v = lo_v; v < hi_v; ++v) {
;           const float pvv = __builtin_amdgcn_exp2f(sc[v >> 4][v & 15] * c - mc);
;           sc[v >> 4][v & 15] = pvv;
;           ps0 += pvv;
;         }
;         if (i >= NPV) {
;           const int plo = (i == NPV) ? 0 : (lo_v >> 1), phi = hi_v >> 1;
; #pragma unroll
;           for (int pi = plo; pi < phi; ++pi) ppu[pi] = pack2(sc[(2 * pi) >> 4][(2 * pi) & 15], sc[(2 * pi + 1) >> 4][(2 * pi + 1) & 15]);
;         }
;         __builtin_amdgcn_sched_barrier(0);
;       }
;       l = l * alpha + ps0;
;       if (do_qk) mxc = rowmax(sn);
;       if (__any(alpha < 1.f)) {
; #pragma unroll
;         for (int d = 0; d < NDT; ++d)
; #pragma unroll
;           for (int q = 0; q < 16; ++q) o[d][q] *= alpha;
;       }
;       asm volatile("s_waitcnt vmcnt(0)" ::: "memory");
;       __syncthreads();
.LBB0_179:
	s_waitcnt lgkmcnt(3)
	v_mfma_f32_32x32x16_bf16 v[64:79], v[56:59], v[134:137], v[64:79]
	v_fma_f32 v32, v33, s80, -v97
	ds_read_b128 v[148:151], v102 offset:96
	ds_read_b128 v[152:155], v105 offset:54272
	v_exp_f32_e32 v127, v32
	v_fma_f32 v32, v34, s80, -v97
	v_exp_f32_e32 v128, v32
	v_cvt_pk_bf16_f32 v32, v126, v127
	s_waitcnt lgkmcnt(3)
	v_mfma_f32_32x32x16_bf16 v[80:95], v[138:141], v[144:147], v[80:95]
	v_fma_f32 v33, v35, s80, -v97
	ds_read_b128 v[56:59], v102 offset:6752
	v_exp_f32_e32 v129, v33
	s_nop 0
	v_cvt_pk_bf16_f32 v33, v128, v129
	s_waitcnt lgkmcnt(3)
	v_mfma_f32_32x32x16_bf16 v[64:79], v[60:63], v[144:147], v[64:79]
	v_fma_f32 v34, v36, s80, -v97
	ds_read_b128 v[136:139], v102 offset:128
	ds_read_b128 v[156:159], v105 offset:55296
	v_exp_f32_e32 v130, v34
	v_fma_f32 v34, v37, s80, -v97
	v_exp_f32_e32 v131, v34
	s_nop 0
	v_cvt_pk_bf16_f32 v34, v130, v131
	s_waitcnt lgkmcnt(3)
	v_mfma_f32_32x32x16_bf16 v[80:95], v[148:151], v[152:155], v[80:95]
	v_fma_f32 v35, v38, s80, -v97
	v_exp_f32_e32 v132, v35
	v_fma_f32 v35, v39, s80, -v97
	ds_read_b128 v[60:63], v102 offset:6784
	v_exp_f32_e32 v133, v35
	s_nop 0
	v_cvt_pk_bf16_f32 v35, v132, v133
	s_and_b64 vcc, exec, s[34:35]
	s_cbranch_vccz .LBB0_183
	s_and_b64 vcc, exec, s[50:51]
	s_cbranch_vccnz .Lattn_mlaA_end
	s_add_i32 m0, s76, 0x3400
	s_add_u32 s50, s0, 0xfffd0000
	s_addc_u32 s51, s1, -1
	global_load_lds_dwordx4 v101, s[50:51]
	s_branch .Lattn_mlaA_end
.LBB0_183:
	s_and_b64 vcc, exec, s[48:49]
	s_cbranch_vccnz .Lattn_mlaA_end
	s_add_i32 m0, s76, 0x6400
	s_add_u32 s50, s72, 0xfffe0000
	s_addc_u32 s51, s73, -1
	global_load_lds_dwordx4 v101, s[50:51]
.Lattn_mlaA_end:
	s_waitcnt lgkmcnt(3)
	v_mfma_f32_32x32x16_bf16 v[64:79], v[56:59], v[152:155], v[64:79]
	ds_read_b128 v[144:147], v102 offset:160
	ds_read_b128 v[148:151], v105 offset:56320
	v_fma_f32 v36, v40, s80, -v97
	v_exp_f32_e32 v134, v36
	s_waitcnt lgkmcnt(3)
	v_mfma_f32_32x32x16_bf16 v[80:95], v[136:139], v[156:159], v[80:95]
	v_fma_f32 v36, v41, s80, -v97
	v_exp_f32_e32 v135, v36
	v_fma_f32 v36, v42, s80, -v97
	ds_read_b128 v[56:59], v102 offset:6816
	v_exp_f32_e32 v136, v36
	v_cvt_pk_bf16_f32 v36, v134, v135
	s_waitcnt lgkmcnt(3)
	v_mfma_f32_32x32x16_bf16 v[64:79], v[60:63], v[156:159], v[64:79]
	v_fma_f32 v37, v43, s80, -v97
	v_exp_f32_e32 v137, v37
	s_nop 0
	v_cvt_pk_bf16_f32 v37, v136, v137
	s_waitcnt lgkmcnt(1)
	v_mfma_f32_32x32x16_bf16 v[80:95], v[144:147], v[148:151], v[80:95]
	v_fma_f32 v38, v44, s80, -v97
	v_exp_f32_e32 v138, v38
	v_fma_f32 v38, v45, s80, -v97
	v_exp_f32_e32 v139, v38
	s_nop 0
	v_cvt_pk_bf16_f32 v38, v138, v139
	s_waitcnt lgkmcnt(0)
	v_mfma_f32_32x32x16_bf16 v[64:79], v[56:59], v[148:151], v[64:79]
	v_fma_f32 v39, v46, s80, -v97
	v_exp_f32_e32 v140, v39
	v_fma_f32 v39, v47, s80, -v97
	v_exp_f32_e32 v141, v39
	s_nop 0
	v_cvt_pk_bf16_f32 v39, v140, v141
	s_nop 1
	v_max_f32_e32 v40, v80, v80
	s_nop 4
	v_max_f32_e32 v41, v64, v64
	v_max_f32_e32 v40, v40, v41
	v_max3_f32 v40, v40, v81, v65
	v_max3_f32 v40, v40, v82, v66
	v_max3_f32 v40, v40, v83, v67
	v_max3_f32 v40, v40, v84, v68
	v_max3_f32 v40, v40, v85, v69
	v_max3_f32 v40, v40, v86, v70
	v_max3_f32 v40, v40, v87, v71
	v_max3_f32 v40, v40, v88, v72
	v_max3_f32 v40, v40, v89, v73
	v_max3_f32 v40, v40, v90, v74
	v_max3_f32 v40, v40, v91, v75
	v_max3_f32 v40, v40, v92, v76
	v_max3_f32 v40, v40, v93, v77
	v_max3_f32 v40, v40, v94, v78
	v_max3_f32 v40, v40, v95, v79
	v_exp_f32_e32 v96, v96
	ds_bpermute_b32 v41, v108, v40
	v_cmp_gt_f32_e32 vcc, 1.0, v96
	s_cbranch_vccz .LBB0_188
	v_pk_mul_f32 v[30:31], v[96:97], v[30:31] op_sel_hi:[0,1]
	v_pk_mul_f32 v[28:29], v[96:97], v[28:29] op_sel_hi:[0,1]
	v_pk_mul_f32 v[26:27], v[96:97], v[26:27] op_sel_hi:[0,1]
	v_pk_mul_f32 v[24:25], v[96:97], v[24:25] op_sel_hi:[0,1]
	v_pk_mul_f32 v[22:23], v[96:97], v[22:23] op_sel_hi:[0,1]
	v_pk_mul_f32 v[20:21], v[96:97], v[20:21] op_sel_hi:[0,1]
	v_pk_mul_f32 v[18:19], v[96:97], v[18:19] op_sel_hi:[0,1]
	v_pk_mul_f32 v[16:17], v[96:97], v[16:17] op_sel_hi:[0,1]
	v_pk_mul_f32 v[14:15], v[96:97], v[14:15] op_sel_hi:[0,1]
	v_pk_mul_f32 v[12:13], v[96:97], v[12:13] op_sel_hi:[0,1]
	v_pk_mul_f32 v[10:11], v[96:97], v[10:11] op_sel_hi:[0,1]
	v_pk_mul_f32 v[8:9], v[96:97], v[8:9] op_sel_hi:[0,1]
	v_pk_mul_f32 v[6:7], v[96:97], v[6:7] op_sel_hi:[0,1]
	v_pk_mul_f32 v[4:5], v[96:97], v[4:5] op_sel_hi:[0,1]
	v_pk_mul_f32 v[2:3], v[96:97], v[2:3] op_sel_hi:[0,1]
	v_pk_mul_f32 v[0:1], v[96:97], v[0:1] op_sel_hi:[0,1]
.LBB0_188:
	s_cmp_lt_u32 s82, s84
	s_waitcnt vmcnt(0)
	s_cselect_b64 s[50:51], -1, 0
	v_cndmask_b32_e64 v42, 0, 1, s[50:51]
	v_cmp_ne_u32_e64 s[50:51], 1, v42
	s_waitcnt lgkmcnt(0)
	s_barrier
.LBB0_216:
	v_max3_f32 v97, v142, v40, v41
	v_sub_f32_e32 v40, v142, v97
	v_mul_f32_e32 v165, 0x3e16c740, v40
	ds_read_b64_tr_b16 v[40:41], v107 offset:0
	ds_read_b64_tr_b16 v[42:43], v107 offset:0x600
	ds_read_b64_tr_b16 v[44:45], v107 offset:64
	ds_read_b64_tr_b16 v[46:47], v107 offset:0x640
	ds_read_b64_tr_b16 v[56:57], v107 offset:0xc00
	ds_read_b64_tr_b16 v[58:59], v107 offset:0x1200
	ds_read_b64_tr_b16 v[60:61], v107 offset:0xc40
	ds_read_b64_tr_b16 v[62:63], v107 offset:0x1240
	s_nop 0
	v_add_f32_e32 v110, 0, v110
	v_add_f32_e32 v110, v111, v110
	v_add_f32_e32 v110, v112, v110
	s_waitcnt lgkmcnt(6)
	v_mul_f32_e32 v167, 0x3e16c740, v97
	v_mfma_f32_32x32x16_bf16 v[16:31], v[40:43], v[52:55], v[16:31]
	v_fma_f32 v40, v80, s80, -v167
	v_exp_f32_e32 v142, v40
	ds_read_b64_tr_b16 v[40:41], v107 offset:0x1800
	ds_read_b64_tr_b16 v[42:43], v107 offset:0x1e00
	v_add_f32_e32 v110, v113, v110
	v_add_f32_e32 v110, v114, v110
	v_add_f32_e32 v110, v115, v110
	s_waitcnt lgkmcnt(6)
	v_mfma_f32_32x32x16_bf16 v[0:15], v[44:47], v[52:55], v[0:15]
	v_fma_f32 v44, v81, s80, -v167
	v_exp_f32_e32 v143, v44
	v_fma_f32 v44, v82, s80, -v167
	v_exp_f32_e32 v144, v44
	ds_read_b64_tr_b16 v[44:45], v107 offset:0x1840
	ds_read_b64_tr_b16 v[46:47], v107 offset:0x1e40
	v_add_f32_e32 v110, v116, v110
	v_add_f32_e32 v110, v117, v110
	v_add_f32_e32 v110, v118, v110
	s_waitcnt lgkmcnt(6)
	v_fma_f32 v52, v83, s80, -v167
	v_mfma_f32_32x32x16_bf16 v[16:31], v[56:59], v[48:51], v[16:31]
	v_exp_f32_e32 v145, v52
	s_and_b64 vcc, exec, s[40:41]
	s_cbranch_vccnz .LBB0_192
	s_and_b64 vcc, exec, s[50:51]
	s_cbranch_vccnz .LBB0_195
	s_mov_b32 m0, s25
	s_nop 0
	global_load_lds_dwordx4 v98, s[0:1]
	s_branch .LBB0_195
; template <int DQK, int DV, int NMAPS>
; __device__ __forceinline__ void attn_phase(const AttnArgs& a, unsigned char* smem) {
;     ...
;       auto issue = [&](const int idx) {
;         if (idx < NPV) {
;           if (do_pv) {
;             const int js = idx / NDT, d = idx % NDT;
;             s16x4 lo, hi;
;             asm volatile("ds_read_b64_tr_b16 %0, %1 offset:%2" : "=v"(lo) : "v"(vaddr), "i"((js * 16) * VSB + d * 64) : "memory");
;             asm volatile("ds_read_b64_tr_b16 %0, %1 offset:%2" : "=v"(hi) : "v"(vaddr), "i"((js * 16 + 8) * VSB + d * 64) : "memory");
;             bf16x8 vf; vf[0] = lo[0]; vf[1] = lo[1]; vf[2] = lo[2]; vf[3] = lo[3]; vf[4] = hi[0]; vf[5] = hi[1]; vf[6] = hi[2]; vf[7] = hi[3];
;             fr[idx % (PD + 1)] = vf;
;           }
;         } else if (idx < NMF) {
;           if (do_qk) {
;             const int qi = idx - NPV, ks = qi >> 1, j = qi & 1;
;             fr[idx % (PD + 1)] = *(const bf16x8*)(kp + j * 32 * KSB + ks * 32);
;             if (j == 0) qv[ks % 3] = *(const bf16x8*)(qlds + ks * 1024);
;           }
;         }
;       };
; #pragma unroll
;       for (int i = 0; i < PD; ++i) issue(i);
; #pragma unroll
;       for (int i = 0; i < NMF; ++i) {
;         issue(i + PD);
;         if (i < NPV) {
;           if (do_pv) {
;             const int js = i / NDT, d = i % NDT;
;             union { unsigned u[4]; bf16x8 v; } cv;
; #pragma unroll
;             for (int k = 0; k < 4; ++k) cv.u[k] = ppu[4 * js + k];
;             int nafter = 0;
; #pragma unroll
;             for (int cc = i + 1; cc <= i + PD; ++cc) {
;               if (cc < NPV) nafter += 2;
;               else if (cc < NMF && do_qk) nafter += ((cc - NPV) & 1) ? 1 : 2;
;             }
;             bf16x8 vfr = fr[i % (PD + 1)];
;             asm volatile("s_waitcnt lgkmcnt(%1)" : "+v"(vfr) : "i"(nafter));
;             o[d] = MFMA32(vfr, cv.v, o[d]);
;           }
;         } else {
;           if (do_qk) {
;             const int qi = i - NPV, ks = qi >> 1, j = qi & 1;
;             if (ks == 0) {
;               f32x16 z;
; #pragma unroll
;               for (int q = 0; q < 16; ++q) z[q] = 0.f;
;               sn[j] = MFMA32(fr[i % (PD + 1)], qv[ks % 3], z);
;             } else sn[j] = MFMA32(fr[i % (PD + 1)], qv[ks % 3], sn[j]);
;           }
;         }
;         const int lo_v = i * 32 / NMF, hi_v = (i + 1) * 32 / NMF;
; #pragma unroll
.LBB0_192:
	s_and_b64 vcc, exec, s[42:43]
	s_cbranch_vccnz .LBB0_195
	s_add_i32 m0, s25, 0x3400
	s_nop 0
	global_load_lds_dwordx4 v98, s[72:73]
.LBB0_195:
	ds_read_b64_tr_b16 v[52:53], v107 offset:0x2400
	ds_read_b64_tr_b16 v[54:55], v107 offset:0x2a00
	v_add_f32_e32 v110, v119, v110
	v_add_f32_e32 v110, v120, v110
	v_add_f32_e32 v110, v121, v110
	s_waitcnt lgkmcnt(6)
	v_mfma_f32_32x32x16_bf16 v[0:15], v[60:63], v[48:51], v[0:15]
	v_fma_f32 v48, v84, s80, -v167
	v_exp_f32_e32 v146, v48
	v_fma_f32 v48, v85, s80, -v167
	v_exp_f32_e32 v147, v48
	ds_read_b64_tr_b16 v[48:49], v107 offset:0x2440
	ds_read_b64_tr_b16 v[50:51], v107 offset:0x2a40
	v_add_f32_e32 v110, v122, v110
	v_add_f32_e32 v110, v123, v110
	v_add_f32_e32 v110, v124, v110
	s_waitcnt lgkmcnt(6)
	v_mfma_f32_32x32x16_bf16 v[16:31], v[40:43], v[32:35], v[16:31]
	v_fma_f32 v40, v86, s80, -v167
	v_exp_f32_e32 v148, v40
	v_fma_f32 v40, v87, s80, -v167
	v_exp_f32_e32 v149, v40
	ds_read_b128 v[40:43], v102 offset:13312
	ds_read_b128 v[150:153], v105 offset:51200
	v_add_f32_e32 v110, v125, v110
	v_add_f32_e32 v110, v126, v110
	v_add_f32_e32 v110, v127, v110
	s_waitcnt lgkmcnt(6)
	v_mfma_f32_32x32x16_bf16 v[0:15], v[44:47], v[32:35], v[0:15]
	v_fma_f32 v32, v88, s80, -v167
	v_exp_f32_e32 v88, v32
	ds_read_b128 v[32:35], v102 offset:19968
	v_add_f32_e32 v110, v128, v110
	v_add_f32_e32 v110, v129, v110
	v_add_f32_e32 v110, v130, v110
	s_waitcnt lgkmcnt(5)
	v_fma_f32 v44, v89, s80, -v167
	v_mfma_f32_32x32x16_bf16 v[16:31], v[52:55], v[36:39], v[16:31]
	v_exp_f32_e32 v89, v44
	v_fma_f32 v44, v90, s80, -v167
	v_exp_f32_e32 v90, v44
	s_and_b64 vcc, exec, s[26:27]
	s_cbranch_vccz .LBB0_199
	s_and_b64 vcc, exec, s[50:51]
	s_cbranch_vccnz .LBB0_202
	s_mov_b32 m0, s29
	s_nop 0
	global_load_lds_dwordx4 v99, s[0:1]
	s_branch .LBB0_202
.LBB0_199:
	s_and_b64 vcc, exec, s[44:45]
	s_cbranch_vccnz .LBB0_202
	s_add_i32 m0, s29, 0x3400
	s_nop 0
	global_load_lds_dwordx4 v99, s[72:73]
.LBB0_202:
	ds_read_b128 v[154:157], v102 offset:13344
	ds_read_b128 v[168:171], v105 offset:52224
	v_add_f32_e32 v110, v131, v110
	v_add_f32_e32 v110, v132, v110
	v_add_f32_e32 v110, v133, v110
	s_waitcnt lgkmcnt(5)
	v_mfma_f32_32x32x16_bf16 v[0:15], v[48:51], v[36:39], v[0:15]
	v_fma_f32 v36, v91, s80, -v167
	v_exp_f32_e32 v91, v36
	v_add_f32_e32 v110, v134, v110
	v_add_f32_e32 v110, v135, v110
	v_add_f32_e32 v110, v136, v110
	s_waitcnt lgkmcnt(3)
	v_mfma_f32_32x32x16_bf16 v[48:63], v[40:43], v[150:153], 0
	v_fma_f32 v36, v92, s80, -v167
	v_exp_f32_e32 v92, v36
	v_fma_f32 v36, v93, s80, -v167
	ds_read_b128 v[172:175], v102 offset:20000
	v_exp_f32_e32 v93, v36
	v_cvt_pk_bf16_f32 v84, v142, v143
	v_cvt_pk_bf16_f32 v85, v144, v145
	v_cvt_pk_bf16_f32 v86, v146, v147
	v_cvt_pk_bf16_f32 v87, v148, v149
	v_cvt_pk_bf16_f32 v80, v88, v89
	v_cvt_pk_bf16_f32 v81, v90, v91
	v_cvt_pk_bf16_f32 v82, v92, v93
	v_fma_f32 v36, v94, s80, -v167
	v_exp_f32_e32 v94, v36
	v_fma_f32 v36, v95, s80, -v167
	v_exp_f32_e32 v95, v36
	v_add_f32_e32 v110, v137, v110
	v_add_f32_e32 v110, v138, v110
	v_add_f32_e32 v110, v139, v110
	s_waitcnt lgkmcnt(3)
	v_mfma_f32_32x32x16_bf16 v[32:47], v[32:35], v[150:153], 0
	ds_read_b128 v[176:179], v102 offset:13376
	ds_read_b128 v[180:183], v105 offset:53248
	v_cvt_pk_bf16_f32 v83, v94, v95
	v_add_f32_e32 v110, v140, v110
	v_add_f32_e32 v110, v141, v110
	v_fmac_f32_e32 v110, v109, v96
	s_waitcnt lgkmcnt(3)
	v_mfma_f32_32x32x16_bf16 v[48:63], v[154:157], v[168:171], v[48:63]
	v_fma_f32 v64, v64, s80, -v167
	ds_read_b128 v[206:209], v102 offset:20032
	v_exp_f32_e32 v150, v64
	s_and_b64 vcc, exec, s[30:31]
	s_cbranch_vccz .LBB0_206
	s_and_b64 vcc, exec, s[50:51]
	s_cbranch_vccnz .LBB0_209
	s_mov_b32 m0, s33
	s_nop 0
	global_load_lds_dwordx4 v100, s[0:1]
	s_branch .LBB0_209
.LBB0_206:
	s_and_b64 vcc, exec, s[46:47]
	s_cbranch_vccnz .LBB0_209
	s_add_i32 m0, s33, 0x3400
	s_nop 0
	global_load_lds_dwordx4 v100, s[72:73]
; __device__ __forceinline__ unsigned pack2(float a, float b) { unsigned r; asm("s_nop 1\n\tv_cvt_pk_bf16_f32 %0, %1, %2" : "=v"(r) : "v"(a), "v"(b)); return r; }
; #define MX3(a_, b_, c_) __builtin_fmaxf(__builtin_fmaxf((a_), (b_)), (c_))
; template <int DQK, int DV, int NMAPS>
; __device__ __forceinline__ void attn_phase(const AttnArgs& a, unsigned char* smem) {
;     ...
;     auto rowmax = [&](const f32x16 (&sx)[2]) -> float {
;     ...
;       float mx = MX3(sx[0][0], sx[1][0], sx[0][1]);
;       mx = MX3(mx, sx[1][1], sx[0][2]);
; #pragma unroll
;       for (int q = 2; q < 15; ++q) mx = MX3(mx, sx[1][q], sx[0][q + 1]);
;       mx = __builtin_fmaxf(mx, sx[1][15]);
;     ...
;       return __builtin_fmaxf(mx, __shfl_xor(mx, 32));
;     };
;     ...
;         const int lo_v = i * 32 / NMF, hi_v = (i + 1) * 32 / NMF;
; #pragma unroll
;         for (int v = lo_v; v < hi_v; ++v) {
;           const float pvv = __builtin_amdgcn_exp2f(sc[v >> 4][v & 15] * c - mc);
;           sc[v >> 4][v & 15] = pvv;
;           ps0 += pvv;
;         }
;         if (i >= NPV) {
;           const int plo = (i == NPV) ? 0 : (lo_v >> 1), phi = hi_v >> 1;
; #pragma unroll
;           for (int pi = plo; pi < phi; ++pi) ppu[pi] = pack2(sc[(2 * pi) >> 4][(2 * pi) & 15], sc[(2 * pi + 1) >> 4][(2 * pi + 1) & 15]);
;         }
;         __builtin_amdgcn_sched_barrier(0);
;       }
;       l = l * alpha + ps0;
;       if (do_qk) mxc = rowmax(sn);
;       if (__any(alpha < 1.f)) {
; #pragma unroll
;         for (int d = 0; d < NDT; ++d)
; #pragma unroll
;           for (int q = 0; q < 16; ++q) o[d][q] *= alpha;
.LBB0_209:
	v_add_f32_e32 v96, 0, v142
	v_add_f32_e32 v96, v143, v96
	v_add_f32_e32 v96, v144, v96
	s_waitcnt lgkmcnt(3)
	v_mfma_f32_32x32x16_bf16 v[32:47], v[172:175], v[168:171], v[32:47]
	v_fma_f32 v64, v65, s80, -v167
	ds_read_b128 v[156:159], v102 offset:13408
	ds_read_b128 v[210:213], v105 offset:54272
	v_exp_f32_e32 v151, v64
	v_fma_f32 v64, v66, s80, -v167
	v_exp_f32_e32 v152, v64
	v_cvt_pk_bf16_f32 v64, v150, v151
	v_add_f32_e32 v96, v145, v96
	v_add_f32_e32 v96, v146, v96
	v_add_f32_e32 v96, v147, v96
	s_waitcnt lgkmcnt(3)
	v_mfma_f32_32x32x16_bf16 v[48:63], v[176:179], v[180:183], v[48:63]
	v_fma_f32 v65, v67, s80, -v167
	ds_read_b128 v[168:171], v102 offset:20064
	v_exp_f32_e32 v153, v65
	s_nop 0
	v_cvt_pk_bf16_f32 v65, v152, v153
	v_add_f32_e32 v96, v148, v96
	v_add_f32_e32 v96, v149, v96
	v_add_f32_e32 v88, v88, v96
	s_waitcnt lgkmcnt(3)
	v_mfma_f32_32x32x16_bf16 v[32:47], v[206:209], v[180:183], v[32:47]
	v_fma_f32 v66, v68, s80, -v167
	ds_read_b128 v[172:175], v102 offset:13440
	ds_read_b128 v[176:179], v105 offset:55296
	v_exp_f32_e32 v154, v66
	v_fma_f32 v66, v69, s80, -v167
	v_exp_f32_e32 v155, v66
	s_nop 0
	v_cvt_pk_bf16_f32 v66, v154, v155
	v_add_f32_e32 v88, v89, v88
	v_add_f32_e32 v88, v90, v88
	v_add_f32_e32 v88, v91, v88
	s_waitcnt lgkmcnt(3)
	v_mfma_f32_32x32x16_bf16 v[48:63], v[156:159], v[210:213], v[48:63]
	v_fma_f32 v67, v70, s80, -v167
	v_exp_f32_e32 v156, v67
	v_fma_f32 v67, v71, s80, -v167
	ds_read_b128 v[180:183], v102 offset:20096
	v_exp_f32_e32 v157, v67
	s_nop 0
	v_cvt_pk_bf16_f32 v67, v156, v157
	s_and_b64 vcc, exec, s[34:35]
	s_cbranch_vccz .LBB0_213
	s_and_b64 vcc, exec, s[50:51]
	s_cbranch_vccnz .Lattn_mlaB_end
	s_mov_b32 m0, s76
	s_nop 0
	global_load_lds_dwordx4 v101, s[0:1]
	s_branch .Lattn_mlaB_end
.LBB0_213:
	s_and_b64 vcc, exec, s[48:49]
	s_cbranch_vccnz .Lattn_mlaB_end
	s_add_i32 m0, s76, 0x3400
	s_nop 0
	global_load_lds_dwordx4 v101, s[72:73]
.Lattn_mlaB_end:
	v_add_f32_e32 v88, v92, v88
	v_add_f32_e32 v88, v93, v88
	v_add_f32_e32 v88, v94, v88
	s_waitcnt lgkmcnt(3)
	v_mfma_f32_32x32x16_bf16 v[32:47], v[168:171], v[210:213], v[32:47]
	ds_read_b128 v[206:209], v102 offset:13472
	ds_read_b128 v[214:217], v105 offset:56320
	v_fma_f32 v68, v72, s80, -v167
	v_exp_f32_e32 v158, v68
	v_add_f32_e32 v88, v95, v88
	v_add_f32_e32 v88, v150, v88
	v_add_f32_e32 v88, v151, v88
	s_waitcnt lgkmcnt(3)
	v_mfma_f32_32x32x16_bf16 v[48:63], v[172:175], v[176:179], v[48:63]
	v_fma_f32 v68, v73, s80, -v167
	v_exp_f32_e32 v73, v68
	v_fma_f32 v68, v74, s80, -v167
	ds_read_b128 v[168:171], v102 offset:20128
	v_exp_f32_e32 v74, v68
	v_cvt_pk_bf16_f32 v68, v158, v73
	v_add_f32_e32 v88, v152, v88
	v_add_f32_e32 v88, v153, v88
	v_add_f32_e32 v88, v154, v88
	s_waitcnt lgkmcnt(3)
	v_mfma_f32_32x32x16_bf16 v[32:47], v[180:183], v[176:179], v[32:47]
	v_fma_f32 v69, v75, s80, -v167
	v_exp_f32_e32 v75, v69
	s_nop 0
	v_cvt_pk_bf16_f32 v69, v74, v75
	v_add_f32_e32 v88, v155, v88
	v_add_f32_e32 v88, v156, v88
	v_add_f32_e32 v88, v157, v88
	s_waitcnt lgkmcnt(1)
	v_mfma_f32_32x32x16_bf16 v[48:63], v[206:209], v[214:217], v[48:63]
	v_fma_f32 v70, v76, s80, -v167
	v_exp_f32_e32 v76, v70
	v_fma_f32 v70, v77, s80, -v167
	v_exp_f32_e32 v77, v70
	s_nop 0
	v_cvt_pk_bf16_f32 v70, v76, v77
	v_add_f32_e32 v88, v158, v88
	s_waitcnt lgkmcnt(0)
	v_mfma_f32_32x32x16_bf16 v[32:47], v[168:171], v[214:217], v[32:47]
	v_fma_f32 v71, v78, s80, -v167
	v_exp_f32_e32 v78, v71
	v_fma_f32 v71, v79, s80, -v167
	v_exp_f32_e32 v79, v71
	s_nop 0
	v_cvt_pk_bf16_f32 v71, v78, v79
	v_exp_f32_e32 v72, v165
	s_nop 0
	v_max_f32_e32 v159, v48, v48
	s_nop 4
	v_max_f32_e32 v165, v32, v32
	v_max_f32_e32 v159, v159, v165
	v_max3_f32 v159, v159, v49, v33
	v_max3_f32 v159, v159, v50, v34
	v_max3_f32 v159, v159, v51, v35
	v_max3_f32 v159, v159, v52, v36
	v_max3_f32 v159, v159, v53, v37
	v_max3_f32 v159, v159, v54, v38
	v_max3_f32 v159, v159, v55, v39
	v_max3_f32 v159, v159, v56, v40
	v_max3_f32 v159, v159, v57, v41
	v_max3_f32 v159, v159, v58, v42
	v_max3_f32 v159, v159, v59, v43
	v_max3_f32 v159, v159, v60, v44
	v_max3_f32 v159, v159, v61, v45
	v_max3_f32 v159, v159, v62, v46
	v_max3_f32 v159, v159, v63, v47
	ds_bpermute_b32 v165, v108, v159
	v_cmp_gt_f32_e32 vcc, 1.0, v72
	s_cbranch_vccz .LBB0_157
	v_pk_mul_f32 v[30:31], v[72:73], v[30:31] op_sel_hi:[0,1]
	v_pk_mul_f32 v[28:29], v[72:73], v[28:29] op_sel_hi:[0,1]
	v_pk_mul_f32 v[26:27], v[72:73], v[26:27] op_sel_hi:[0,1]
	v_pk_mul_f32 v[24:25], v[72:73], v[24:25] op_sel_hi:[0,1]
	v_pk_mul_f32 v[22:23], v[72:73], v[22:23] op_sel_hi:[0,1]
	v_pk_mul_f32 v[20:21], v[72:73], v[20:21] op_sel_hi:[0,1]
	v_pk_mul_f32 v[18:19], v[72:73], v[18:19] op_sel_hi:[0,1]
	v_pk_mul_f32 v[16:17], v[72:73], v[16:17] op_sel_hi:[0,1]
	v_pk_mul_f32 v[14:15], v[72:73], v[14:15] op_sel_hi:[0,1]
	v_pk_mul_f32 v[12:13], v[72:73], v[12:13] op_sel_hi:[0,1]
	v_pk_mul_f32 v[10:11], v[72:73], v[10:11] op_sel_hi:[0,1]
	v_pk_mul_f32 v[8:9], v[72:73], v[8:9] op_sel_hi:[0,1]
	v_pk_mul_f32 v[6:7], v[72:73], v[6:7] op_sel_hi:[0,1]
	v_pk_mul_f32 v[4:5], v[72:73], v[4:5] op_sel_hi:[0,1]
	v_pk_mul_f32 v[2:3], v[72:73], v[2:3] op_sel_hi:[0,1]
	v_pk_mul_f32 v[0:1], v[72:73], v[0:1] op_sel_hi:[0,1]
	s_branch .LBB0_157

; template <int DQK, int DV, int NMAPS>
; __device__ __forceinline__ void attn_phase(const AttnArgs& a, unsigned char* smem) {
;     ...
;     auto dma = [&](bool wantk, int kt, int kb, bool wantv, int vt, int vb) {
; #pragma unroll
;       for (int i = 0; i < NDI; ++i) {
;         const int idx = wave + 8 * i;
;         if (idx < NKI) {
;           if (wantk) glds16s(Kg + (size_t)kt * 64 * a.ldk, (unsigned)doff[i], (unsigned)__builtin_amdgcn_readfirstlane(lds0 + kb * KBYTES + idx * 1024));
;         } else if (idx < NKI + NVI) {
;     ...
; #pragma unroll
;       for (int i = 0; i < PD; ++i) issue(i);
; #pragma unroll
;       for (int i = 0; i < NMF; ++i) {
;         issue(i + PD);
;         if (i < NPV) {
;           if (do_pv) {
;             const int js = i / NDT, d = i % NDT;
;             union { unsigned u[4]; bf16x8 v; } cv;
; #pragma unroll
;             for (int k = 0; k < 4; ++k) cv.u[k] = ppu[4 * js + k];
;             int nafter = 0;
; #pragma unroll
;             for (int cc = i + 1; cc <= i + PD; ++cc) {
;               if (cc < NPV) nafter += 2;
;               else if (cc < NMF && do_qk) nafter += ((cc - NPV) & 1) ? 1 : 2;
;             }
;             bf16x8 vfr = fr[i % (PD + 1)];
;             asm volatile("s_waitcnt lgkmcnt(%1)" : "+v"(vfr) : "i"(nafter));
;             o[d] = MFMA32(vfr, cv.v, o[d]);
;           }
;         } else {
;           if (do_qk) {
;             const int qi = i - NPV, ks = qi >> 1, j = qi & 1;
;             if (ks == 0) {
;               f32x16 z;
; #pragma unroll
;               for (int q = 0; q < 16; ++q) z[q] = 0.f;
;               sn[j] = MFMA32(fr[i % (PD + 1)], qv[ks % 3], z);
;             } else sn[j] = MFMA32(fr[i % (PD + 1)], qv[ks % 3], sn[j]);
;           }
;         }
;         const int lo_v = i * 32 / NMF, hi_v = (i + 1) * 32 / NMF;
; #pragma unroll
;         for (int v = lo_v; v < hi_v; ++v) {
;           const float pvv = __builtin_amdgcn_exp2f(sc[v >> 4][v & 15] * c - mc);
;           sc[v >> 4][v & 15] = pvv;
;           ps0 += pvv;
;         }
;         if (i >= NPV) {
;           const int plo = (i == NPV) ? 0 : (lo_v >> 1), phi = hi_v >> 1;
; #pragma unroll
;           for (int pi = plo; pi < phi; ++pi) ppu[pi] = pack2(sc[(2 * pi) >> 4][(2 * pi) & 15], sc[(2 * pi + 1) >> 4][(2 * pi + 1) & 15]);
;         }
;         __builtin_amdgcn_sched_barrier(0);
;       }
;       l = l * alpha + ps0;
.LBB0_302:
	v_add_f32_e32 v118, v216, v118
	v_add_f32_e32 v118, v217, v118
	v_add_f32_e32 v101, v101, v118
	v_add_f32_e32 v101, v102, v101
	v_add_f32_e32 v101, v103, v101
	s_add_u32 s92, s92, 0xc0000
	v_add_f32_e32 v101, v104, v101
	s_addc_u32 s93, s93, 0
	s_add_i32 s82, s82, 2
	v_add_f32_e32 v141, v105, v101
	s_waitcnt vmcnt(0)
	s_add_u32 s94, s94, 0xc0000
	v_fmac_f32_e32 v141, v142, v100
	s_waitcnt lgkmcnt(0)
	v_max_f32_e32 v100, v219, v219
	v_max_f32_e32 v101, v218, v218
	s_addc_u32 s95, s95, 0
	v_max_f32_e32 v100, v101, v100
	s_cmp_ge_u32 s87, s86
	s_barrier
	s_cbranch_scc1 .LBB0_377
.LBB0_303:
	s_add_i32 s87, s82, -1
	s_cmp_lt_u32 s87, s84
	s_cselect_b64 s[52:53], -1, 0
	v_cndmask_b32_e64 v101, 0, 1, s[52:53]
	v_cmp_ne_u32_e64 s[52:53], 1, v101
.LBB0_338:
	v_max_f32_e32 v100, v100, v100
	v_max_f32_e32 v101, v127, v127
	v_max_f32_e32 v180, v101, v100
	v_sub_f32_e32 v100, v127, v180
	v_mul_f32_e32 v126, 0x3e38aa3b, v100
	ds_read_b64_tr_b16 v[100:101], v137 offset:0
	ds_read_b64_tr_b16 v[102:103], v137 offset:0xa00
	ds_read_b64_tr_b16 v[118:119], v137 offset:64
	ds_read_b64_tr_b16 v[120:121], v137 offset:0xa40
	ds_read_b64_tr_b16 v[122:123], v137 offset:0x80
	ds_read_b64_tr_b16 v[124:125], v137 offset:0xa80
	ds_read_b64_tr_b16 v[146:147], v137 offset:0xc0
	ds_read_b64_tr_b16 v[148:149], v137 offset:0xac0
	s_nop 0
	s_waitcnt lgkmcnt(6)
	v_mul_f32_e32 v127, 0x3e38aa3b, v180
	v_mfma_f32_32x32x16_bf16 v[48:63], v[100:103], v[114:117], v[48:63]
	v_fma_f32 v80, v80, s6, -v127
	v_exp_f32_e32 v142, v80
	ds_read_b64_tr_b16 v[100:101], v137 offset:0x1400
	ds_read_b64_tr_b16 v[102:103], v137 offset:0x1e00
	s_waitcnt lgkmcnt(6)
	v_fma_f32 v80, v81, s6, -v127
	v_mfma_f32_32x32x16_bf16 v[32:47], v[118:121], v[114:117], v[32:47]
	v_exp_f32_e32 v143, v80
	ds_read_b64_tr_b16 v[118:119], v137 offset:0x1440
	ds_read_b64_tr_b16 v[120:121], v137 offset:0x1e40
	s_waitcnt lgkmcnt(6)
	v_fma_f32 v80, v82, s6, -v127
	v_mfma_f32_32x32x16_bf16 v[16:31], v[122:125], v[114:117], v[16:31]
	v_exp_f32_e32 v144, v80
	v_fma_f32 v80, v83, s6, -v127
	v_exp_f32_e32 v145, v80
	s_and_b64 vcc, exec, s[40:41]
	s_cbranch_vccnz .LBB0_307
	s_and_b64 vcc, exec, s[52:53]
	s_cbranch_vccnz .LBB0_310
	s_add_i32 m0, s25, 0x4400
	s_add_u32 s72, s92, 0xfffa0000
	s_addc_u32 s73, s93, -1
	global_load_lds_dwordx4 v132, s[72:73]
	s_branch .LBB0_310
.LBB0_307:
	s_and_b64 vcc, exec, s[42:43]
	s_cbranch_vccnz .LBB0_310
	s_add_i32 m0, s25, 0x9400
	s_add_u32 s72, s94, 0xfffa0000
	s_addc_u32 s73, s95, -1
	global_load_lds_dwordx4 v132, s[72:73]
.LBB0_310:
	ds_read_b64_tr_b16 v[80:81], v137 offset:0x1480
	ds_read_b64_tr_b16 v[82:83], v137 offset:0x1e80
	s_waitcnt lgkmcnt(6)
	v_fma_f32 v84, v84, s6, -v127
	v_mfma_f32_32x32x16_bf16 v[0:15], v[146:149], v[114:117], v[0:15]
	v_exp_f32_e32 v146, v84
	ds_read_b64_tr_b16 v[114:115], v137 offset:0x14c0
	ds_read_b64_tr_b16 v[116:117], v137 offset:0x1ec0
	s_waitcnt lgkmcnt(6)
	v_fma_f32 v84, v85, s6, -v127
	v_mfma_f32_32x32x16_bf16 v[48:63], v[100:103], v[110:113], v[48:63]
	v_exp_f32_e32 v147, v84
	ds_read_b64_tr_b16 v[100:101], v137 offset:0x2800
	ds_read_b64_tr_b16 v[102:103], v137 offset:0x3200
	s_waitcnt lgkmcnt(6)
	v_fma_f32 v84, v86, s6, -v127
	v_mfma_f32_32x32x16_bf16 v[32:47], v[118:121], v[110:113], v[32:47]
	v_exp_f32_e32 v148, v84
	v_fma_f32 v84, v87, s6, -v127
	v_exp_f32_e32 v149, v84
	s_and_b64 vcc, exec, s[36:37]
	s_cbranch_vccz .LBB0_314
	s_and_b64 vcc, exec, s[52:53]
	s_cbranch_vccnz .LBB0_317
	s_add_i32 m0, s29, 0x4400
	s_add_u32 s72, s92, 0xfffa0000
	s_addc_u32 s73, s93, -1
	global_load_lds_dwordx4 v131, s[72:73]
	s_branch .LBB0_317
.LBB0_314:
	s_and_b64 vcc, exec, s[44:45]
	s_cbranch_vccnz .LBB0_317
	s_add_i32 m0, s29, 0x9400
	s_add_u32 s72, s94, 0xfffa0000
	s_addc_u32 s73, s95, -1
	global_load_lds_dwordx4 v131, s[72:73]
.LBB0_317:
	ds_read_b64_tr_b16 v[84:85], v137 offset:0x2840
	ds_read_b64_tr_b16 v[86:87], v137 offset:0x3240
	s_waitcnt lgkmcnt(6)
	v_mfma_f32_32x32x16_bf16 v[16:31], v[80:83], v[110:113], v[16:31]
	v_fma_f32 v80, v88, s6, -v127
	v_exp_f32_e32 v150, v80
	ds_read_b64_tr_b16 v[80:81], v137 offset:0x2880
	ds_read_b64_tr_b16 v[82:83], v137 offset:0x3280
	s_waitcnt lgkmcnt(6)
	v_fma_f32 v88, v89, s6, -v127
	v_mfma_f32_32x32x16_bf16 v[0:15], v[114:117], v[110:113], v[0:15]
	v_exp_f32_e32 v151, v88
	ds_read_b64_tr_b16 v[110:111], v137 offset:0x28c0
	ds_read_b64_tr_b16 v[112:113], v137 offset:0x32c0
	s_waitcnt lgkmcnt(6)
	v_fma_f32 v88, v90, s6, -v127
	v_mfma_f32_32x32x16_bf16 v[48:63], v[100:103], v[106:109], v[48:63]
	v_exp_f32_e32 v152, v88
	v_fma_f32 v88, v91, s6, -v127
	v_exp_f32_e32 v153, v88
	s_and_b64 vcc, exec, s[38:39]
	s_cbranch_vccz .LBB0_321
	s_and_b64 vcc, exec, s[52:53]
	s_cbranch_vccnz .LBB0_324
	s_add_i32 m0, s33, 0x4400
	s_add_u32 s72, s92, 0xfffa0000
	s_addc_u32 s73, s93, -1
	global_load_lds_dwordx4 v130, s[72:73]
	s_branch .LBB0_324
.LBB0_321:
	s_and_b64 vcc, exec, s[46:47]
	s_cbranch_vccnz .LBB0_324
	s_add_i32 m0, s33, 0x9400
	s_add_u32 s72, s94, 0xfffa0000
	s_addc_u32 s73, s95, -1
	global_load_lds_dwordx4 v130, s[72:73]
.LBB0_324:
	ds_read_b64_tr_b16 v[88:89], v137 offset:0x3c00
	ds_read_b64_tr_b16 v[90:91], v137 offset:0x4600
	s_waitcnt lgkmcnt(6)
	v_mfma_f32_32x32x16_bf16 v[32:47], v[84:87], v[106:109], v[32:47]
	v_fma_f32 v84, v92, s6, -v127
	v_exp_f32_e32 v154, v84
	ds_read_b64_tr_b16 v[84:85], v137 offset:0x3c40
	ds_read_b64_tr_b16 v[86:87], v137 offset:0x4640
	s_waitcnt lgkmcnt(6)
	v_mfma_f32_32x32x16_bf16 v[16:31], v[80:83], v[106:109], v[16:31]
	v_fma_f32 v80, v93, s6, -v127
	v_exp_f32_e32 v155, v80
	ds_read_b64_tr_b16 v[80:81], v137 offset:0x3c80
	ds_read_b64_tr_b16 v[82:83], v137 offset:0x4680
	s_waitcnt lgkmcnt(6)
	v_fma_f32 v92, v94, s6, -v127
	v_mfma_f32_32x32x16_bf16 v[0:15], v[110:113], v[106:109], v[0:15]
	v_exp_f32_e32 v156, v92
	v_fma_f32 v92, v95, s6, -v127
	v_exp_f32_e32 v157, v92
	s_and_b64 vcc, exec, s[54:55]
	s_cbranch_vccz .LBB0_328
	s_and_b64 vcc, exec, s[52:53]
	s_cbranch_vccnz .LBB0_331
	s_add_i32 m0, s74, 0x4400
	s_add_u32 s72, s92, 0xfffa0000
	s_addc_u32 s73, s93, -1
	global_load_lds_dwordx4 v129, s[72:73]
	s_branch .LBB0_331
; template <int DQK, int DV, int NMAPS>
; __device__ __forceinline__ void attn_phase(const AttnArgs& a, unsigned char* smem) {
;     ...
;     auto dma = [&](bool wantk, int kt, int kb, bool wantv, int vt, int vb) {
; #pragma unroll
;       for (int i = 0; i < NDI; ++i) {
;         const int idx = wave + 8 * i;
;         if (idx < NKI) {
;     ...
; #pragma unroll
;       for (int i = 0; i < PD; ++i) issue(i);
; #pragma unroll
;       for (int i = 0; i < NMF; ++i) {
;         issue(i + PD);
;         if (i < NPV) {
;           if (do_pv) {
;             const int js = i / NDT, d = i % NDT;
;             union { unsigned u[4]; bf16x8 v; } cv;
; #pragma unroll
;             for (int k = 0; k < 4; ++k) cv.u[k] = ppu[4 * js + k];
;             int nafter = 0;
; #pragma unroll
;             for (int cc = i + 1; cc <= i + PD; ++cc) {
;               if (cc < NPV) nafter += 2;
;               else if (cc < NMF && do_qk) nafter += ((cc - NPV) & 1) ? 1 : 2;
;             }
;             bf16x8 vfr = fr[i % (PD + 1)];
;             asm volatile("s_waitcnt lgkmcnt(%1)" : "+v"(vfr) : "i"(nafter));
;             o[d] = MFMA32(vfr, cv.v, o[d]);
;           }
;         } else {
;           if (do_qk) {
;             const int qi = i - NPV, ks = qi >> 1, j = qi & 1;
;             if (ks == 0) {
;               f32x16 z;
; #pragma unroll
;               for (int q = 0; q < 16; ++q) z[q] = 0.f;
;               sn[j] = MFMA32(fr[i % (PD + 1)], qv[ks % 3], z);
;             } else sn[j] = MFMA32(fr[i % (PD + 1)], qv[ks % 3], sn[j]);
;           }
;         }
;         const int lo_v = i * 32 / NMF, hi_v = (i + 1) * 32 / NMF;
; #pragma unroll
;         for (int v = lo_v; v < hi_v; ++v) {
;           const float pvv = __builtin_amdgcn_exp2f(sc[v >> 4][v & 15] * c - mc);
;           sc[v >> 4][v & 15] = pvv;
;           ps0 += pvv;
;         }
;         if (i >= NPV) {
;           const int plo = (i == NPV) ? 0 : (lo_v >> 1), phi = hi_v >> 1;
; #pragma unroll
;           for (int pi = plo; pi < phi; ++pi) ppu[pi] = pack2(sc[(2 * pi) >> 4][(2 * pi) & 15], sc[(2 * pi + 1) >> 4][(2 * pi + 1) & 15]);
;         }
;         __builtin_amdgcn_sched_barrier(0);
;       }
;       l = l * alpha + ps0;
;       if (do_qk) mxc = rowmax(sn);
;       if (__any(alpha < 1.f)) {
; #pragma unroll
;         for (int d = 0; d < NDT; ++d)
; #pragma unroll
;           for (int q = 0; q < 16; ++q) o[d][q] *= alpha;
.LBB0_328:
	s_and_b64 vcc, exec, s[48:49]
	s_cbranch_vccnz .LBB0_331
	s_add_i32 m0, s74, 0x9400
	s_add_u32 s72, s94, 0xfffa0000
	s_addc_u32 s73, s95, -1
	global_load_lds_dwordx4 v129, s[72:73]
.LBB0_331:
	ds_read_b64_tr_b16 v[92:93], v137 offset:0x3cc0
	ds_read_b64_tr_b16 v[94:95], v137 offset:0x46c0
	s_waitcnt lgkmcnt(6)
	v_fma_f32 v64, v64, s6, -v127
	v_mfma_f32_32x32x16_bf16 v[48:63], v[88:91], v[96:99], v[48:63]
	v_exp_f32_e32 v158, v64
	ds_read_b128 v[88:91], v135
	ds_read_b128 v[100:103], v139
	s_waitcnt lgkmcnt(6)
	v_fma_f32 v64, v65, s6, -v127
	v_mfma_f32_32x32x16_bf16 v[32:47], v[84:87], v[96:99], v[32:47]
	v_exp_f32_e32 v159, v64
	ds_read_b128 v[172:175], v135 offset:8704
	s_waitcnt lgkmcnt(5)
	v_fma_f32 v64, v66, s6, -v127
	v_mfma_f32_32x32x16_bf16 v[16:31], v[80:83], v[96:99], v[16:31]
	v_exp_f32_e32 v165, v64
	v_fma_f32 v64, v67, s6, -v127
	v_exp_f32_e32 v167, v64
	s_and_b64 vcc, exec, s[88:89]
	s_cbranch_vccz .LBB0_335
	s_and_b64 vcc, exec, s[52:53]
	s_cbranch_vccnz .Lattn_daA_end
	s_add_i32 m0, s75, 0x4400
	s_add_u32 s52, s92, 0xfffa0000
	s_addc_u32 s53, s93, -1
	global_load_lds_dwordx4 v128, s[52:53]
	s_branch .Lattn_daA_end
.LBB0_335:
	s_and_b64 vcc, exec, s[50:51]
	s_cbranch_vccnz .Lattn_daA_end
	s_add_i32 m0, s75, 0x9400
	s_add_u32 s52, s94, 0xfffa0000
	s_addc_u32 s53, s95, -1
	global_load_lds_dwordx4 v128, s[52:53]
.Lattn_daA_end:
	ds_read_b128 v[64:67], v135 offset:32
	ds_read_b128 v[176:179], v139 offset:1024
	s_waitcnt lgkmcnt(5)
	v_fma_f32 v68, v68, s6, -v127
	v_mfma_f32_32x32x16_bf16 v[0:15], v[92:95], v[96:99], v[0:15]
	v_exp_f32_e32 v168, v68
	s_waitcnt lgkmcnt(3)
	v_mfma_f32_32x32x16_bf16 v[106:121], v[88:91], v[100:103], 0
	v_fma_f32 v68, v69, s6, -v127
	ds_read_b128 v[182:185], v135 offset:8736
	v_exp_f32_e32 v169, v68
	v_cvt_pk_bf16_f32 v122, v142, v143
	v_cvt_pk_bf16_f32 v123, v144, v145
	v_cvt_pk_bf16_f32 v124, v146, v147
	v_cvt_pk_bf16_f32 v125, v148, v149
	v_cvt_pk_bf16_f32 v84, v150, v151
	v_cvt_pk_bf16_f32 v85, v152, v153
	v_cvt_pk_bf16_f32 v86, v154, v155
	v_cvt_pk_bf16_f32 v87, v156, v157
	v_cvt_pk_bf16_f32 v80, v158, v159
	v_cvt_pk_bf16_f32 v81, v165, v167
	v_cvt_pk_bf16_f32 v82, v168, v169
	s_waitcnt lgkmcnt(3)
	v_mfma_f32_32x32x16_bf16 v[90:105], v[172:175], v[100:103], 0
	v_fma_f32 v68, v70, s6, -v127
	ds_read_b128 v[206:209], v135 offset:64
	ds_read_b128 v[210:213], v139 offset:2048
	v_exp_f32_e32 v170, v68
	v_fma_f32 v68, v71, s6, -v127
	v_exp_f32_e32 v171, v68
	s_nop 0
	v_cvt_pk_bf16_f32 v83, v170, v171
	s_waitcnt lgkmcnt(3)
	v_mfma_f32_32x32x16_bf16 v[106:121], v[64:67], v[176:179], v[106:121]
	ds_read_b128 v[68:71], v135 offset:8768
	v_fma_f32 v64, v72, s6, -v127
	v_exp_f32_e32 v172, v64
	s_waitcnt lgkmcnt(3)
	v_mfma_f32_32x32x16_bf16 v[90:105], v[182:185], v[176:179], v[90:105]
	ds_read_b128 v[214:217], v135 offset:96
	ds_read_b128 v[218:221], v139 offset:3072
	v_fma_f32 v64, v73, s6, -v127
	v_exp_f32_e32 v173, v64
	s_nop 0
	v_cvt_pk_bf16_f32 v64, v172, v173
	s_waitcnt lgkmcnt(3)
	v_mfma_f32_32x32x16_bf16 v[106:121], v[206:209], v[210:213], v[106:121]
	v_fma_f32 v65, v74, s6, -v127
	v_exp_f32_e32 v174, v65
	v_fma_f32 v65, v75, s6, -v127
	ds_read_b128 v[182:185], v135 offset:8800
	v_exp_f32_e32 v175, v65
	s_nop 0
	v_cvt_pk_bf16_f32 v65, v174, v175
	s_waitcnt lgkmcnt(3)
	v_mfma_f32_32x32x16_bf16 v[90:105], v[68:71], v[210:213], v[90:105]
	v_fma_f32 v66, v76, s6, -v127
	v_exp_f32_e32 v176, v66
	s_waitcnt lgkmcnt(1)
	v_mfma_f32_32x32x16_bf16 v[106:121], v[214:217], v[218:221], v[106:121]
	v_fma_f32 v66, v77, s6, -v127
	v_exp_f32_e32 v177, v66
	s_nop 0
	v_cvt_pk_bf16_f32 v66, v176, v177
	s_waitcnt lgkmcnt(0)
	v_mfma_f32_32x32x16_bf16 v[90:105], v[182:185], v[218:221], v[90:105]
	v_fma_f32 v67, v78, s6, -v127
	v_exp_f32_e32 v178, v67
	v_fma_f32 v67, v79, s6, -v127
	v_exp_f32_e32 v179, v67
	s_nop 0
	v_cvt_pk_bf16_f32 v67, v178, v179
	s_nop 3
	v_max_f32_e32 v68, v106, v106
	s_nop 2
	v_max_f32_e32 v69, v90, v90
	v_max_f32_e32 v68, v68, v69
	v_max3_f32 v68, v68, v107, v91
	v_max3_f32 v68, v68, v108, v92
	v_max3_f32 v68, v68, v109, v93
	v_max3_f32 v68, v68, v110, v94
	v_max3_f32 v68, v68, v111, v95
	v_max3_f32 v68, v68, v112, v96
	v_max3_f32 v68, v68, v113, v97
	v_max3_f32 v68, v68, v114, v98
	v_max3_f32 v68, v68, v115, v99
	v_max3_f32 v68, v68, v116, v100
	v_max3_f32 v68, v68, v117, v101
	v_max3_f32 v68, v68, v118, v102
	v_max3_f32 v68, v68, v119, v103
	v_max3_f32 v68, v68, v120, v104
	v_max3_f32 v68, v68, v121, v105
	v_exp_f32_e32 v126, v126
	ds_bpermute_b32 v69, v140, v68
	v_cmp_gt_f32_e32 vcc, 1.0, v126
	s_cbranch_vccz .LBB0_340
	v_pk_mul_f32 v[62:63], v[126:127], v[62:63] op_sel_hi:[0,1]
	v_pk_mul_f32 v[60:61], v[126:127], v[60:61] op_sel_hi:[0,1]
	v_pk_mul_f32 v[58:59], v[126:127], v[58:59] op_sel_hi:[0,1]
	v_pk_mul_f32 v[56:57], v[126:127], v[56:57] op_sel_hi:[0,1]
	v_pk_mul_f32 v[54:55], v[126:127], v[54:55] op_sel_hi:[0,1]
	v_pk_mul_f32 v[52:53], v[126:127], v[52:53] op_sel_hi:[0,1]
	v_pk_mul_f32 v[50:51], v[126:127], v[50:51] op_sel_hi:[0,1]
	v_pk_mul_f32 v[48:49], v[126:127], v[48:49] op_sel_hi:[0,1]
	v_pk_mul_f32 v[46:47], v[126:127], v[46:47] op_sel_hi:[0,1]
	v_pk_mul_f32 v[44:45], v[126:127], v[44:45] op_sel_hi:[0,1]
	v_pk_mul_f32 v[42:43], v[126:127], v[42:43] op_sel_hi:[0,1]
	v_pk_mul_f32 v[40:41], v[126:127], v[40:41] op_sel_hi:[0,1]
	v_pk_mul_f32 v[38:39], v[126:127], v[38:39] op_sel_hi:[0,1]
	v_pk_mul_f32 v[36:37], v[126:127], v[36:37] op_sel_hi:[0,1]
	v_pk_mul_f32 v[34:35], v[126:127], v[34:35] op_sel_hi:[0,1]
	v_pk_mul_f32 v[32:33], v[126:127], v[32:33] op_sel_hi:[0,1]
	v_pk_mul_f32 v[30:31], v[126:127], v[30:31] op_sel_hi:[0,1]
	v_pk_mul_f32 v[28:29], v[126:127], v[28:29] op_sel_hi:[0,1]
	v_pk_mul_f32 v[26:27], v[126:127], v[26:27] op_sel_hi:[0,1]
	v_pk_mul_f32 v[24:25], v[126:127], v[24:25] op_sel_hi:[0,1]
	v_pk_mul_f32 v[22:23], v[126:127], v[22:23] op_sel_hi:[0,1]
	v_pk_mul_f32 v[20:21], v[126:127], v[20:21] op_sel_hi:[0,1]
	v_pk_mul_f32 v[18:19], v[126:127], v[18:19] op_sel_hi:[0,1]
	v_pk_mul_f32 v[16:17], v[126:127], v[16:17] op_sel_hi:[0,1]
	v_pk_mul_f32 v[14:15], v[126:127], v[14:15] op_sel_hi:[0,1]
	v_pk_mul_f32 v[12:13], v[126:127], v[12:13] op_sel_hi:[0,1]
	v_pk_mul_f32 v[10:11], v[126:127], v[10:11] op_sel_hi:[0,1]
	v_pk_mul_f32 v[8:9], v[126:127], v[8:9] op_sel_hi:[0,1]
	v_pk_mul_f32 v[6:7], v[126:127], v[6:7] op_sel_hi:[0,1]
	v_pk_mul_f32 v[4:5], v[126:127], v[4:5] op_sel_hi:[0,1]
	v_pk_mul_f32 v[2:3], v[126:127], v[2:3] op_sel_hi:[0,1]
	v_pk_mul_f32 v[0:1], v[126:127], v[0:1] op_sel_hi:[0,1]
; template <int DQK, int DV, int NMAPS>
; __device__ __forceinline__ void attn_phase(const AttnArgs& a, unsigned char* smem) {
;     ...
;       auto issue = [&](const int idx) {
;         if (idx < NPV) {
;           if (do_pv) {
;             const int js = idx / NDT, d = idx % NDT;
;             s16x4 lo, hi;
;             asm volatile("ds_read_b64_tr_b16 %0, %1 offset:%2" : "=v"(lo) : "v"(vaddr), "i"((js * 16) * VSB + d * 64) : "memory");
;             asm volatile("ds_read_b64_tr_b16 %0, %1 offset:%2" : "=v"(hi) : "v"(vaddr), "i"((js * 16 + 8) * VSB + d * 64) : "memory");
;             bf16x8 vf; vf[0] = lo[0]; vf[1] = lo[1]; vf[2] = lo[2]; vf[3] = lo[3]; vf[4] = hi[0]; vf[5] = hi[1]; vf[6] = hi[2]; vf[7] = hi[3];
;             fr[idx % (PD + 1)] = vf;
;           }
;         } else if (idx < NMF) {
;           if (do_qk) {
;             const int qi = idx - NPV, ks = qi >> 1, j = qi & 1;
;             fr[idx % (PD + 1)] = *(const bf16x8*)(kp + j * 32 * KSB + ks * 32);
;             if (j == 0) qv[ks % 3] = *(const bf16x8*)(qlds + ks * 1024);
;           }
;         }
;       };
; #pragma unroll
;       for (int i = 0; i < PD; ++i) issue(i);
; #pragma unroll
;       for (int i = 0; i < NMF; ++i) {
;         issue(i + PD);
;         if (i < NPV) {
;           if (do_pv) {
;             const int js = i / NDT, d = i % NDT;
;             union { unsigned u[4]; bf16x8 v; } cv;
; #pragma unroll
;             for (int k = 0; k < 4; ++k) cv.u[k] = ppu[4 * js + k];
;             int nafter = 0;
; #pragma unroll
;             for (int cc = i + 1; cc <= i + PD; ++cc) {
;               if (cc < NPV) nafter += 2;
;               else if (cc < NMF && do_qk) nafter += ((cc - NPV) & 1) ? 1 : 2;
;             }
;             bf16x8 vfr = fr[i % (PD + 1)];
;             asm volatile("s_waitcnt lgkmcnt(%1)" : "+v"(vfr) : "i"(nafter));
;             o[d] = MFMA32(vfr, cv.v, o[d]);
;           }
;         } else {
;           if (do_qk) {
;             const int qi = i - NPV, ks = qi >> 1, j = qi & 1;
;             if (ks == 0) {
;               f32x16 z;
; #pragma unroll
;               for (int q = 0; q < 16; ++q) z[q] = 0.f;
;               sn[j] = MFMA32(fr[i % (PD + 1)], qv[ks % 3], z);
;             } else sn[j] = MFMA32(fr[i % (PD + 1)], qv[ks % 3], sn[j]);
;           }
;         }
;         const int lo_v = i * 32 / NMF, hi_v = (i + 1) * 32 / NMF;
; #pragma unroll
.LBB0_340:
	s_cmp_lt_u32 s82, s84
	s_waitcnt vmcnt(0)
	s_cselect_b64 s[52:53], -1, 0
	v_cndmask_b32_e64 v70, 0, 1, s[52:53]
	v_cmp_ne_u32_e64 s[52:53], 1, v70
	s_waitcnt lgkmcnt(0)
	s_barrier
.LBB0_375:
	v_max3_f32 v127, v180, v68, v69
	v_sub_f32_e32 v68, v180, v127
	v_mul_f32_e32 v248, 0x3e38aa3b, v68
	ds_read_b64_tr_b16 v[68:69], v138 offset:0
	ds_read_b64_tr_b16 v[70:71], v138 offset:0xa00
	ds_read_b64_tr_b16 v[72:73], v138 offset:64
	ds_read_b64_tr_b16 v[74:75], v138 offset:0xa40
	ds_read_b64_tr_b16 v[76:77], v138 offset:0x80
	ds_read_b64_tr_b16 v[78:79], v138 offset:0xa80
	ds_read_b64_tr_b16 v[206:207], v138 offset:0xc0
	ds_read_b64_tr_b16 v[208:209], v138 offset:0xac0
	s_nop 0
	v_add_f32_e32 v142, 0, v142
	v_add_f32_e32 v142, v143, v142
	v_add_f32_e32 v142, v144, v142
	s_waitcnt lgkmcnt(6)
	v_mul_f32_e32 v249, 0x3e38aa3b, v127
	v_mfma_f32_32x32x16_bf16 v[48:63], v[68:71], v[122:125], v[48:63]
	v_fma_f32 v68, v106, s6, -v249
	v_exp_f32_e32 v180, v68
	ds_read_b64_tr_b16 v[68:69], v138 offset:0x1400
	ds_read_b64_tr_b16 v[70:71], v138 offset:0x1e00
	v_add_f32_e32 v142, v145, v142
	v_add_f32_e32 v142, v146, v142
	v_add_f32_e32 v142, v147, v142
	s_waitcnt lgkmcnt(6)
	v_mfma_f32_32x32x16_bf16 v[32:47], v[72:75], v[122:125], v[32:47]
	v_fma_f32 v72, v107, s6, -v249
	v_exp_f32_e32 v181, v72
	ds_read_b64_tr_b16 v[72:73], v138 offset:0x1440
	ds_read_b64_tr_b16 v[74:75], v138 offset:0x1e40
	v_add_f32_e32 v142, v148, v142
	v_add_f32_e32 v142, v149, v142
	v_add_f32_e32 v142, v150, v142
	s_waitcnt lgkmcnt(6)
	v_mfma_f32_32x32x16_bf16 v[16:31], v[76:79], v[122:125], v[16:31]
	v_fma_f32 v76, v108, s6, -v249
	v_exp_f32_e32 v182, v76
	v_fma_f32 v76, v109, s6, -v249
	v_exp_f32_e32 v183, v76
	s_and_b64 vcc, exec, s[40:41]
	s_cbranch_vccnz .LBB0_344
	s_and_b64 vcc, exec, s[52:53]
	s_cbranch_vccnz .LBB0_347
	s_mov_b32 m0, s25
	s_nop 0
	global_load_lds_dwordx4 v132, s[92:93]
	s_branch .LBB0_347
.LBB0_344:
	s_and_b64 vcc, exec, s[42:43]
	s_cbranch_vccnz .LBB0_347
	s_add_i32 m0, s25, 0x4400
	s_nop 0
	global_load_lds_dwordx4 v132, s[94:95]
.LBB0_347:
	ds_read_b64_tr_b16 v[76:77], v138 offset:0x1480
	ds_read_b64_tr_b16 v[78:79], v138 offset:0x1e80
	v_add_f32_e32 v142, v151, v142
	v_add_f32_e32 v142, v152, v142
	v_add_f32_e32 v142, v153, v142
	s_waitcnt lgkmcnt(6)
	v_fma_f32 v88, v110, s6, -v249
	v_mfma_f32_32x32x16_bf16 v[0:15], v[206:209], v[122:125], v[0:15]
	v_exp_f32_e32 v122, v88
	ds_read_b64_tr_b16 v[106:107], v138 offset:0x14c0
	ds_read_b64_tr_b16 v[108:109], v138 offset:0x1ec0
	v_add_f32_e32 v142, v154, v142
	v_add_f32_e32 v142, v155, v142
	v_add_f32_e32 v142, v156, v142
	s_waitcnt lgkmcnt(6)
	v_mfma_f32_32x32x16_bf16 v[48:63], v[68:71], v[84:87], v[48:63]
	v_fma_f32 v68, v111, s6, -v249
	v_exp_f32_e32 v123, v68
	ds_read_b64_tr_b16 v[68:69], v138 offset:0x2800
	ds_read_b64_tr_b16 v[70:71], v138 offset:0x3200
	v_add_f32_e32 v142, v157, v142
	v_add_f32_e32 v142, v158, v142
	v_add_f32_e32 v142, v159, v142
	s_waitcnt lgkmcnt(6)
	v_mfma_f32_32x32x16_bf16 v[32:47], v[72:75], v[84:87], v[32:47]
	v_fma_f32 v72, v112, s6, -v249
	v_exp_f32_e32 v124, v72
	v_fma_f32 v72, v113, s6, -v249
	v_exp_f32_e32 v125, v72
	s_and_b64 vcc, exec, s[36:37]
	s_cbranch_vccz .LBB0_351
	s_and_b64 vcc, exec, s[52:53]
	s_cbranch_vccnz .LBB0_354
	s_mov_b32 m0, s29
	s_nop 0
	global_load_lds_dwordx4 v131, s[92:93]
	s_branch .LBB0_354
.LBB0_351:
	s_and_b64 vcc, exec, s[44:45]
	s_cbranch_vccnz .LBB0_354
	s_add_i32 m0, s29, 0x4400
	s_nop 0
	global_load_lds_dwordx4 v131, s[94:95]
.LBB0_354:
	ds_read_b64_tr_b16 v[72:73], v138 offset:0x2840
	ds_read_b64_tr_b16 v[74:75], v138 offset:0x3240
	v_add_f32_e32 v142, v165, v142
	v_add_f32_e32 v142, v167, v142
	v_add_f32_e32 v142, v168, v142
	s_waitcnt lgkmcnt(6)
	v_mfma_f32_32x32x16_bf16 v[16:31], v[76:79], v[84:87], v[16:31]
	v_fma_f32 v76, v114, s6, -v249
	v_exp_f32_e32 v184, v76
	ds_read_b64_tr_b16 v[76:77], v138 offset:0x2880
	ds_read_b64_tr_b16 v[78:79], v138 offset:0x3280
	v_add_f32_e32 v142, v169, v142
	v_add_f32_e32 v142, v170, v142
	v_add_f32_e32 v142, v171, v142
	s_waitcnt lgkmcnt(6)
	v_mfma_f32_32x32x16_bf16 v[0:15], v[106:109], v[84:87], v[0:15]
	v_fma_f32 v84, v115, s6, -v249
	v_exp_f32_e32 v185, v84
	ds_read_b64_tr_b16 v[84:85], v138 offset:0x28c0
	ds_read_b64_tr_b16 v[86:87], v138 offset:0x32c0
	v_add_f32_e32 v142, v172, v142
	v_add_f32_e32 v142, v173, v142
	v_add_f32_e32 v142, v174, v142
	s_waitcnt lgkmcnt(6)
	v_mfma_f32_32x32x16_bf16 v[48:63], v[68:71], v[80:83], v[48:63]
	v_fma_f32 v68, v116, s6, -v249
	v_exp_f32_e32 v205, v68
	v_fma_f32 v68, v117, s6, -v249
	v_exp_f32_e32 v206, v68
	s_and_b64 vcc, exec, s[38:39]
	s_cbranch_vccz .LBB0_358
	s_and_b64 vcc, exec, s[52:53]
	s_cbranch_vccnz .LBB0_361
	s_mov_b32 m0, s33
	s_nop 0
	global_load_lds_dwordx4 v130, s[92:93]
	s_branch .LBB0_361
.LBB0_358:
	s_and_b64 vcc, exec, s[46:47]
	s_cbranch_vccnz .LBB0_361
	s_add_i32 m0, s33, 0x4400
	s_nop 0
	global_load_lds_dwordx4 v130, s[94:95]
.LBB0_361:
	ds_read_b64_tr_b16 v[68:69], v138 offset:0x3c00
	ds_read_b64_tr_b16 v[70:71], v138 offset:0x4600
	v_add_f32_e32 v142, v175, v142
	v_add_f32_e32 v142, v176, v142
	v_add_f32_e32 v142, v177, v142
	s_waitcnt lgkmcnt(6)
	v_mfma_f32_32x32x16_bf16 v[32:47], v[72:75], v[80:83], v[32:47]
	v_fma_f32 v72, v118, s6, -v249
	v_exp_f32_e32 v118, v72
	ds_read_b64_tr_b16 v[72:73], v138 offset:0x3c40
	ds_read_b64_tr_b16 v[74:75], v138 offset:0x4640
	v_add_f32_e32 v142, v178, v142
	v_add_f32_e32 v142, v179, v142
	v_fmac_f32_e32 v142, v141, v126
	s_waitcnt lgkmcnt(6)
	v_mfma_f32_32x32x16_bf16 v[16:31], v[76:79], v[80:83], v[16:31]
	v_fma_f32 v76, v119, s6, -v249
	v_exp_f32_e32 v119, v76
	ds_read_b64_tr_b16 v[76:77], v138 offset:0x3c80
	ds_read_b64_tr_b16 v[78:79], v138 offset:0x4680
	v_add_f32_e32 v126, 0, v180
	v_add_f32_e32 v126, v181, v126
	v_add_f32_e32 v126, v182, v126
	s_waitcnt lgkmcnt(6)
	v_mfma_f32_32x32x16_bf16 v[0:15], v[84:87], v[80:83], v[0:15]
	v_fma_f32 v80, v120, s6, -v249
	v_exp_f32_e32 v120, v80
	v_fma_f32 v80, v121, s6, -v249
	v_exp_f32_e32 v121, v80
	s_and_b64 vcc, exec, s[54:55]
	s_cbranch_vccz .LBB0_365
	s_and_b64 vcc, exec, s[52:53]
	s_cbranch_vccnz .LBB0_368
	s_mov_b32 m0, s74
	s_nop 0
	global_load_lds_dwordx4 v129, s[92:93]
	s_branch .LBB0_368
; #define MFMA32(a, b, c) __builtin_amdgcn_mfma_f32_32x32x16_bf16(a, b, c, 0, 0, 0)
; template <int DQK, int DV, int NMAPS>
; __device__ __forceinline__ void attn_phase(const AttnArgs& a, unsigned char* smem) {
;     ...
;     auto dma = [&](bool wantk, int kt, int kb, bool wantv, int vt, int vb) {
; #pragma unroll
;       for (int i = 0; i < NDI; ++i) {
;         const int idx = wave + 8 * i;
;         if (idx < NKI) {
;           if (wantk) glds16s(Kg + (size_t)kt * 64 * a.ldk, (unsigned)doff[i], (unsigned)__builtin_amdgcn_readfirstlane(lds0 + kb * KBYTES + idx * 1024));
;         } else if (idx < NKI + NVI) {
;     ...
;       auto issue = [&](const int idx) {
;         if (idx < NPV) {
;           if (do_pv) {
;             const int js = idx / NDT, d = idx % NDT;
;             s16x4 lo, hi;
;             asm volatile("ds_read_b64_tr_b16 %0, %1 offset:%2" : "=v"(lo) : "v"(vaddr), "i"((js * 16) * VSB + d * 64) : "memory");
;             asm volatile("ds_read_b64_tr_b16 %0, %1 offset:%2" : "=v"(hi) : "v"(vaddr), "i"((js * 16 + 8) * VSB + d * 64) : "memory");
;             bf16x8 vf; vf[0] = lo[0]; vf[1] = lo[1]; vf[2] = lo[2]; vf[3] = lo[3]; vf[4] = hi[0]; vf[5] = hi[1]; vf[6] = hi[2]; vf[7] = hi[3];
;             fr[idx % (PD + 1)] = vf;
;           }
;         } else if (idx < NMF) {
;           if (do_qk) {
;             const int qi = idx - NPV, ks = qi >> 1, j = qi & 1;
;             fr[idx % (PD + 1)] = *(const bf16x8*)(kp + j * 32 * KSB + ks * 32);
;             if (j == 0) qv[ks % 3] = *(const bf16x8*)(qlds + ks * 1024);
;           }
;         }
;       };
; #pragma unroll
;       for (int i = 0; i < PD; ++i) issue(i);
; #pragma unroll
;       for (int i = 0; i < NMF; ++i) {
;         issue(i + PD);
;         if (i < NPV) {
;           if (do_pv) {
;             const int js = i / NDT, d = i % NDT;
;             union { unsigned u[4]; bf16x8 v; } cv;
; #pragma unroll
;             for (int k = 0; k < 4; ++k) cv.u[k] = ppu[4 * js + k];
;             int nafter = 0;
; #pragma unroll
;             for (int cc = i + 1; cc <= i + PD; ++cc) {
;               if (cc < NPV) nafter += 2;
;               else if (cc < NMF && do_qk) nafter += ((cc - NPV) & 1) ? 1 : 2;
;             }
;             bf16x8 vfr = fr[i % (PD + 1)];
;             asm volatile("s_waitcnt lgkmcnt(%1)" : "+v"(vfr) : "i"(nafter));
;             o[d] = MFMA32(vfr, cv.v, o[d]);
;           }
.LBB0_365:
	s_and_b64 vcc, exec, s[48:49]
	s_cbranch_vccnz .LBB0_368
	s_add_i32 m0, s74, 0x4400
	s_nop 0
	global_load_lds_dwordx4 v129, s[94:95]
.LBB0_368:
	ds_read_b64_tr_b16 v[80:81], v138 offset:0x3cc0
	ds_read_b64_tr_b16 v[82:83], v138 offset:0x46c0
	v_add_f32_e32 v126, v183, v126
	s_waitcnt lgkmcnt(6)
	v_mfma_f32_32x32x16_bf16 v[48:63], v[68:71], v[64:67], v[48:63]
	v_fma_f32 v68, v90, s6, -v249
	v_exp_f32_e32 v207, v68
	ds_read_b128 v[68:71], v135 offset:17408
	ds_read_b128 v[216:219], v139
	s_waitcnt lgkmcnt(6)
	v_mfma_f32_32x32x16_bf16 v[32:47], v[72:75], v[64:67], v[32:47]
	v_fma_f32 v72, v91, s6, -v249
	v_exp_f32_e32 v208, v72
	ds_read_b128 v[72:75], v135 offset:26112
	s_waitcnt lgkmcnt(5)
	v_mfma_f32_32x32x16_bf16 v[16:31], v[76:79], v[64:67], v[16:31]
	v_fma_f32 v76, v92, s6, -v249
	v_exp_f32_e32 v209, v76
	v_fma_f32 v76, v93, s6, -v249
	v_exp_f32_e32 v210, v76
	s_and_b64 vcc, exec, s[88:89]
	s_cbranch_vccz .LBB0_372
	s_and_b64 vcc, exec, s[52:53]
	s_cbranch_vccnz .Lattn_daB_end
	s_mov_b32 m0, s75
	s_nop 0
	global_load_lds_dwordx4 v128, s[92:93]
	s_branch .Lattn_daB_end
.LBB0_372:
	s_and_b64 vcc, exec, s[50:51]
	s_cbranch_vccnz .Lattn_daB_end
	s_add_i32 m0, s75, 0x4400
	s_nop 0
	global_load_lds_dwordx4 v128, s[94:95]
; __device__ __forceinline__ unsigned pack2(float a, float b) { unsigned r; asm("s_nop 1\n\tv_cvt_pk_bf16_f32 %0, %1, %2" : "=v"(r) : "v"(a), "v"(b)); return r; }
; #define MX3(a_, b_, c_) __builtin_fmaxf(__builtin_fmaxf((a_), (b_)), (c_))
; template <int DQK, int DV, int NMAPS>
; __device__ __forceinline__ void attn_phase(const AttnArgs& a, unsigned char* smem) {
;     ...
;     auto rowmax = [&](const f32x16 (&sx)[2]) -> float {
;     ...
;       float mx = MX3(sx[0][0], sx[1][0], sx[0][1]);
;       mx = MX3(mx, sx[1][1], sx[0][2]);
; #pragma unroll
;       for (int q = 2; q < 15; ++q) mx = MX3(mx, sx[1][q], sx[0][q + 1]);
;       mx = __builtin_fmaxf(mx, sx[1][15]);
;     ...
;       return __builtin_fmaxf(mx, __shfl_xor(mx, 32));
;     };
;     ...
;         const int lo_v = i * 32 / NMF, hi_v = (i + 1) * 32 / NMF;
; #pragma unroll
;         for (int v = lo_v; v < hi_v; ++v) {
;           const float pvv = __builtin_amdgcn_exp2f(sc[v >> 4][v & 15] * c - mc);
;           sc[v >> 4][v & 15] = pvv;
;           ps0 += pvv;
;         }
;         if (i >= NPV) {
;           const int plo = (i == NPV) ? 0 : (lo_v >> 1), phi = hi_v >> 1;
; #pragma unroll
;           for (int pi = plo; pi < phi; ++pi) ppu[pi] = pack2(sc[(2 * pi) >> 4][(2 * pi) & 15], sc[(2 * pi + 1) >> 4][(2 * pi + 1) & 15]);
;         }
;         __builtin_amdgcn_sched_barrier(0);
;       }
;       l = l * alpha + ps0;
;       if (do_qk) mxc = rowmax(sn);
;       if (__any(alpha < 1.f)) {
; #pragma unroll
;         for (int d = 0; d < NDT; ++d)
; #pragma unroll
;           for (int q = 0; q < 16; ++q) o[d][q] *= alpha;
.Lattn_daB_end:
	ds_read_b128 v[220:223], v135 offset:17440
	ds_read_b128 v[224:227], v139 offset:1024
	s_waitcnt lgkmcnt(5)
	v_mfma_f32_32x32x16_bf16 v[0:15], v[80:83], v[64:67], v[0:15]
	v_fma_f32 v64, v94, s6, -v249
	v_exp_f32_e32 v211, v64
	v_fma_f32 v64, v95, s6, -v249
	s_waitcnt lgkmcnt(3)
	v_mfma_f32_32x32x16_bf16 v[80:95], v[68:71], v[216:219], 0
	ds_read_b128 v[228:231], v135 offset:26144
	v_exp_f32_e32 v212, v64
	v_cvt_pk_bf16_f32 v114, v180, v181
	v_cvt_pk_bf16_f32 v115, v182, v183
	v_cvt_pk_bf16_f32 v116, v122, v123
	v_cvt_pk_bf16_f32 v117, v124, v125
	v_cvt_pk_bf16_f32 v110, v184, v185
	v_cvt_pk_bf16_f32 v111, v205, v206
	v_cvt_pk_bf16_f32 v112, v118, v119
	v_cvt_pk_bf16_f32 v113, v120, v121
	v_cvt_pk_bf16_f32 v106, v207, v208
	v_cvt_pk_bf16_f32 v107, v209, v210
	v_cvt_pk_bf16_f32 v108, v211, v212
	v_fma_f32 v64, v96, s6, -v249
	v_exp_f32_e32 v213, v64
	v_fma_f32 v64, v97, s6, -v249
	v_exp_f32_e32 v214, v64
	v_add_f32_e32 v122, v122, v126
	v_add_f32_e32 v122, v123, v122
	v_add_f32_e32 v122, v124, v122
	s_waitcnt lgkmcnt(3)
	v_mfma_f32_32x32x16_bf16 v[64:79], v[72:75], v[216:219], 0
	ds_read_b128 v[232:235], v135 offset:17472
	ds_read_b128 v[236:239], v139 offset:2048
	v_cvt_pk_bf16_f32 v109, v213, v214
	v_add_f32_e32 v122, v125, v122
	v_add_f32_e32 v122, v184, v122
	v_add_f32_e32 v122, v185, v122
	s_waitcnt lgkmcnt(3)
	v_mfma_f32_32x32x16_bf16 v[80:95], v[220:223], v[224:227], v[80:95]
	v_fma_f32 v96, v98, s6, -v249
	ds_read_b128 v[240:243], v135 offset:26176
	v_exp_f32_e32 v215, v96
	v_add_f32_e32 v122, v205, v122
	v_add_f32_e32 v122, v206, v122
	v_add_f32_e32 v118, v118, v122
	s_waitcnt lgkmcnt(3)
	v_mfma_f32_32x32x16_bf16 v[64:79], v[228:231], v[224:227], v[64:79]
	ds_read_b128 v[218:221], v135 offset:17504
	ds_read_b128 v[244:247], v139 offset:3072
	v_fma_f32 v96, v99, s6, -v249
	v_exp_f32_e32 v216, v96
	s_nop 0
	v_cvt_pk_bf16_f32 v96, v215, v216
	v_add_f32_e32 v118, v119, v118
	v_add_f32_e32 v118, v120, v118
	v_add_f32_e32 v118, v121, v118
	s_waitcnt lgkmcnt(3)
	v_mfma_f32_32x32x16_bf16 v[80:95], v[232:235], v[236:239], v[80:95]
	v_fma_f32 v97, v100, s6, -v249
	v_exp_f32_e32 v217, v97
	v_fma_f32 v97, v101, s6, -v249
	ds_read_b128 v[222:225], v135 offset:26208
	v_exp_f32_e32 v101, v97
	s_nop 0
	v_cvt_pk_bf16_f32 v97, v217, v101
	v_add_f32_e32 v118, v207, v118
	v_add_f32_e32 v118, v208, v118
	v_add_f32_e32 v118, v209, v118
	s_waitcnt lgkmcnt(3)
	v_mfma_f32_32x32x16_bf16 v[64:79], v[240:243], v[236:239], v[64:79]
	v_fma_f32 v98, v102, s6, -v249
	v_exp_f32_e32 v102, v98
	v_add_f32_e32 v118, v210, v118
	v_add_f32_e32 v118, v211, v118
	v_add_f32_e32 v118, v212, v118
	s_waitcnt lgkmcnt(1)
	v_mfma_f32_32x32x16_bf16 v[80:95], v[218:221], v[244:247], v[80:95]
	v_fma_f32 v98, v103, s6, -v249
	v_exp_f32_e32 v103, v98
	s_nop 0
	v_cvt_pk_bf16_f32 v98, v102, v103
	v_add_f32_e32 v118, v213, v118
	v_add_f32_e32 v118, v214, v118
	v_add_f32_e32 v118, v215, v118
	s_waitcnt lgkmcnt(0)
	v_mfma_f32_32x32x16_bf16 v[64:79], v[222:225], v[244:247], v[64:79]
	v_fma_f32 v99, v104, s6, -v249
	v_exp_f32_e32 v104, v99
	v_fma_f32 v99, v105, s6, -v249
	v_exp_f32_e32 v105, v99
	s_nop 0
	v_cvt_pk_bf16_f32 v99, v104, v105
	s_nop 3
	v_max_f32_e32 v218, v80, v80
	s_nop 2
	v_max_f32_e32 v219, v64, v64
	v_max_f32_e32 v218, v218, v219
	v_max3_f32 v218, v218, v81, v65
	v_max3_f32 v218, v218, v82, v66
	v_max3_f32 v218, v218, v83, v67
	v_max3_f32 v218, v218, v84, v68
	v_max3_f32 v218, v218, v85, v69
	v_max3_f32 v218, v218, v86, v70
	v_max3_f32 v218, v218, v87, v71
	v_max3_f32 v218, v218, v88, v72
	v_max3_f32 v218, v218, v89, v73
	v_max3_f32 v218, v218, v90, v74
	v_max3_f32 v218, v218, v91, v75
	v_max3_f32 v218, v218, v92, v76
	v_max3_f32 v218, v218, v93, v77
	v_max3_f32 v218, v218, v94, v78
	v_max3_f32 v218, v218, v95, v79
	v_exp_f32_e32 v100, v248
	ds_bpermute_b32 v219, v140, v218
	v_cmp_gt_f32_e32 vcc, 1.0, v100
	s_cbranch_vccz .LBB0_302
	v_pk_mul_f32 v[62:63], v[100:101], v[62:63] op_sel_hi:[0,1]
	v_pk_mul_f32 v[60:61], v[100:101], v[60:61] op_sel_hi:[0,1]
	v_pk_mul_f32 v[58:59], v[100:101], v[58:59] op_sel_hi:[0,1]
	v_pk_mul_f32 v[56:57], v[100:101], v[56:57] op_sel_hi:[0,1]
	v_pk_mul_f32 v[54:55], v[100:101], v[54:55] op_sel_hi:[0,1]
	v_pk_mul_f32 v[52:53], v[100:101], v[52:53] op_sel_hi:[0,1]
	v_pk_mul_f32 v[50:51], v[100:101], v[50:51] op_sel_hi:[0,1]
	v_pk_mul_f32 v[48:49], v[100:101], v[48:49] op_sel_hi:[0,1]
	v_pk_mul_f32 v[46:47], v[100:101], v[46:47] op_sel_hi:[0,1]
	v_pk_mul_f32 v[44:45], v[100:101], v[44:45] op_sel_hi:[0,1]
	v_pk_mul_f32 v[42:43], v[100:101], v[42:43] op_sel_hi:[0,1]
	v_pk_mul_f32 v[40:41], v[100:101], v[40:41] op_sel_hi:[0,1]
	v_pk_mul_f32 v[38:39], v[100:101], v[38:39] op_sel_hi:[0,1]
	v_pk_mul_f32 v[36:37], v[100:101], v[36:37] op_sel_hi:[0,1]
	v_pk_mul_f32 v[34:35], v[100:101], v[34:35] op_sel_hi:[0,1]
	v_pk_mul_f32 v[32:33], v[100:101], v[32:33] op_sel_hi:[0,1]
	v_pk_mul_f32 v[30:31], v[100:101], v[30:31] op_sel_hi:[0,1]
	v_pk_mul_f32 v[28:29], v[100:101], v[28:29] op_sel_hi:[0,1]
	v_pk_mul_f32 v[26:27], v[100:101], v[26:27] op_sel_hi:[0,1]
	v_pk_mul_f32 v[24:25], v[100:101], v[24:25] op_sel_hi:[0,1]
	v_pk_mul_f32 v[22:23], v[100:101], v[22:23] op_sel_hi:[0,1]
	v_pk_mul_f32 v[20:21], v[100:101], v[20:21] op_sel_hi:[0,1]
	v_pk_mul_f32 v[18:19], v[100:101], v[18:19] op_sel_hi:[0,1]
	v_pk_mul_f32 v[16:17], v[100:101], v[16:17] op_sel_hi:[0,1]
	v_pk_mul_f32 v[14:15], v[100:101], v[14:15] op_sel_hi:[0,1]
	v_pk_mul_f32 v[12:13], v[100:101], v[12:13] op_sel_hi:[0,1]
	v_pk_mul_f32 v[10:11], v[100:101], v[10:11] op_sel_hi:[0,1]
	v_pk_mul_f32 v[8:9], v[100:101], v[8:9] op_sel_hi:[0,1]
	v_pk_mul_f32 v[6:7], v[100:101], v[6:7] op_sel_hi:[0,1]
	v_pk_mul_f32 v[4:5], v[100:101], v[4:5] op_sel_hi:[0,1]
	v_pk_mul_f32 v[2:3], v[100:101], v[2:3] op_sel_hi:[0,1]
	v_pk_mul_f32 v[0:1], v[100:101], v[0:1] op_sel_hi:[0,1]
	s_branch .LBB0_302
